# K-loops: all load-cluster scalar math hoisted into MA-cluster tails only (s98-s101 scratch); MB tails keep only the exit compare
# baseline (speedup 1.0000x reference)
; #define PG8_STAGE(bufoff, gbase, voff) do { _Pragma("unroll") for (int _i = 0; _i < 2; ++_i) \
;         __builtin_amdgcn_global_load_lds((const unsigned*)((const char*)(gbase) + (voff)[_i]), (LAS unsigned*)(lds + (bufoff) + ldsw + _i * 8192), 16, 0, 0); } while (0)
; #define PG8_LDA(dst, b, h) do { _Pragma("unroll") for (int m = 0; m < 4; ++m) _Pragma("unroll") for (int k = 0; k < 2; ++k) dst[m][k] = *(const LAS bf16x8*)(lds + PG8_SA(b, h) + aoff + m * 2048 + k * 1024); } while (0)
; template <class Prog>
; __device__ __forceinline__ void gemm_phase(LAS unsigned char* lds, const int K, const Prog& S) {
;     ...
;     for (;;) {
;         const bool has_next = S.next(ui + 1, nxt);
;         const char* nA = has_next ? nxt.a : cA; const char* nB = has_next ? nxt.b : cB;
;         for (int t = 0; t < nt; t += 2) {
;             const bool last = (t == nt - 2);
;             const char* a1 = cA + (size_t)(t + 1) * kstep;
;             const char* a2 = last ? nA : cA + (size_t)(t + 2) * kstep; const char* b2 = last ? nB : cB + (size_t)(t + 2) * kstep;
;             const char* a3 = a2 + kstep; const char* b3 = b2 + kstep;
;             PG8_LDB(B0, 0, 0); PG8_SCHED; PG8_LDA(At, 0, 0); PG8_STAGE(PG8_SA(1, 1), a1 + hstep, voffA);
;             PG8_WAIT_L(8); PG8_BAR; PG8_WAIT_L(0); PG8_MMA(0, 0, At, B0); PG8_BAR; PG8_SCHED;
;             PG8_LDB(B1, 0, 1); PG8_STAGE(PG8_SB(0, 0), b2, voffB);
;             PG8_BAR; PG8_WAIT_L(0); PG8_MMA(0, 1, At, B1); PG8_BAR;
;             PG8_LDA(At, 0, 1); PG8_STAGE(PG8_SA(0, 0), a2, voffA);
;             PG8_BAR; PG8_WAIT_L(0); PG8_MMA(1, 0, At, B0); PG8_BAR; PG8_SCHED;
;             PG8_STAGE(PG8_SB(0, 1), b2 + hstep, voffB);
;             PG8_WAIT_V(6); PG8_BAR; PG8_MMA(1, 1, At, B1); PG8_BAR;
;             PG8_LDB(B0, 1, 0); PG8_SCHED; PG8_LDA(At, 1, 0); PG8_STAGE(PG8_SA(0, 1), a2 + hstep, voffA);
;             PG8_WAIT_L(8); PG8_BAR; PG8_WAIT_L(0); PG8_MMA(0, 0, At, B0); PG8_BAR; PG8_SCHED;
;             PG8_LDB(B1, 1, 1); PG8_STAGE(PG8_SB(1, 0), b3, voffB);
;             PG8_BAR; PG8_WAIT_L(0); PG8_MMA(0, 1, At, B1); PG8_BAR;
;             PG8_LDA(At, 1, 1); PG8_STAGE(PG8_SA(1, 0), a3, voffA);
;             PG8_BAR; PG8_WAIT_L(0); PG8_MMA(1, 0, At, B0); PG8_BAR; PG8_SCHED;
;             PG8_STAGE(PG8_SB(1, 1), b3 + hstep, voffB);
;             PG8_WAIT_V(6); PG8_BAR; PG8_MMA(1, 1, At, B1); PG8_BAR;
.LBB0_100:
	s_add_u32 s40, s40, 0x80080
	s_addc_u32 s41, s41, 0
	s_add_u32 s9, s44, 0x100
	s_addc_u32 s15, s45, 0
	s_mov_b32 s69, -2
	s_waitcnt vmcnt(16)
	v_add_u32_e32 v244, 0x10000, v205
	s_add_u32 s44, s40, 0xfff80080
	s_addc_u32 s45, s41, -1
	s_cmp_eq_u32 s69, 28
	s_cselect_b32 s47, s5, s45
	s_cselect_b32 s46, s4, s44
	s_cselect_b32 s45, s13, s15
	s_cselect_b32 s44, s12, s9
	s_add_u32 s100, s40, 0xfff80000
	s_addc_u32 s101, s41, -1
	ds_read_b128 v[128:131], v244
	ds_read_b128 v[132:135], v244 offset:1024
	ds_read_b128 v[136:139], v244 offset:2048
	ds_read_b128 v[140:143], v244 offset:3072
	s_add_i32 m0, s92, 0x8000
	ds_read_b128 v[188:191], v244 offset:16384
	ds_read_b128 v[196:199], v244 offset:17408
	ds_read_b128 v[200:203], v244 offset:18432
	ds_read_b128 v[218:221], v244 offset:19456
	global_load_lds_dwordx4 v184, s[100:101]
	s_add_i32 m0, s92, 0xa000
	ds_read_b128 v[144:147], v216
	ds_read_b128 v[148:151], v216 offset:1024
	ds_read_b128 v[152:155], v216 offset:2048
	ds_read_b128 v[156:159], v216 offset:3072
	global_load_lds_dwordx4 v186, s[100:101]
	s_add_i32 m0, s92, 0xc000
	ds_read_b128 v[160:163], v216 offset:4096
	ds_read_b128 v[164:167], v216 offset:5120
	ds_read_b128 v[168:171], v216 offset:6144
	ds_read_b128 v[172:175], v216 offset:7168
	global_load_lds_dwordx4 v184, s[40:41]
	s_add_i32 m0, s92, 0xe000
	s_nop 0
	global_load_lds_dwordx4 v186, s[40:41]
	s_waitcnt lgkmcnt(0)
	s_barrier
	v_mfma_f32_16x16x32_bf16 v[124:127], v[128:131], v[144:147], 0
	v_mfma_f32_16x16x32_bf16 v[116:119], v[136:139], v[144:147], 0
	v_mfma_f32_16x16x32_bf16 v[108:111], v[128:131], v[152:155], 0
	v_mfma_f32_16x16x32_bf16 v[100:103], v[136:139], v[152:155], 0
	v_mfma_f32_16x16x32_bf16 v[92:95], v[128:131], v[160:163], 0
	v_mfma_f32_16x16x32_bf16 v[84:87], v[136:139], v[160:163], 0
	v_mfma_f32_16x16x32_bf16 v[76:79], v[128:131], v[168:171], 0
	v_mfma_f32_16x16x32_bf16 v[68:71], v[136:139], v[168:171], 0
	v_mfma_f32_16x16x32_bf16 v[124:127], v[132:135], v[148:151], v[124:127]
	v_mfma_f32_16x16x32_bf16 v[116:119], v[140:143], v[148:151], v[116:119]
	v_mfma_f32_16x16x32_bf16 v[108:111], v[132:135], v[156:159], v[108:111]
	v_mfma_f32_16x16x32_bf16 v[100:103], v[140:143], v[156:159], v[100:103]
	v_mfma_f32_16x16x32_bf16 v[92:95], v[132:135], v[164:167], v[92:95]
	v_mfma_f32_16x16x32_bf16 v[84:87], v[140:143], v[164:167], v[84:87]
	v_mfma_f32_16x16x32_bf16 v[76:79], v[132:135], v[172:175], v[76:79]
	v_mfma_f32_16x16x32_bf16 v[68:71], v[140:143], v[172:175], v[68:71]
	v_mfma_f32_16x16x32_bf16 v[120:123], v[188:191], v[144:147], 0
	v_mfma_f32_16x16x32_bf16 v[112:115], v[200:203], v[144:147], 0
	v_mfma_f32_16x16x32_bf16 v[104:107], v[188:191], v[152:155], 0
	v_mfma_f32_16x16x32_bf16 v[96:99], v[200:203], v[152:155], 0
	v_mfma_f32_16x16x32_bf16 v[88:91], v[188:191], v[160:163], 0
	v_mfma_f32_16x16x32_bf16 v[80:83], v[200:203], v[160:163], 0
	v_mfma_f32_16x16x32_bf16 v[72:75], v[188:191], v[168:171], 0
	v_mfma_f32_16x16x32_bf16 v[64:67], v[200:203], v[168:171], 0
	v_mfma_f32_16x16x32_bf16 v[120:123], v[196:199], v[148:151], v[120:123]
	v_mfma_f32_16x16x32_bf16 v[112:115], v[218:221], v[148:151], v[112:115]
	v_mfma_f32_16x16x32_bf16 v[104:107], v[196:199], v[156:159], v[104:107]
	v_mfma_f32_16x16x32_bf16 v[96:99], v[218:221], v[156:159], v[96:99]
	v_mfma_f32_16x16x32_bf16 v[88:91], v[196:199], v[164:167], v[88:91]
	v_mfma_f32_16x16x32_bf16 v[80:83], v[218:221], v[164:167], v[80:83]
	v_mfma_f32_16x16x32_bf16 v[72:75], v[196:199], v[172:175], v[72:75]
	v_mfma_f32_16x16x32_bf16 v[64:67], v[218:221], v[172:175], v[64:67]
	s_add_u32 s76, s44, 0x80000
	s_addc_u32 s77, s45, 0
	s_add_u32 s98, s46, 0x80000
	s_addc_u32 s99, s47, 0
	s_barrier
	ds_read_b128 v[144:147], v216 offset:16384
	ds_read_b128 v[148:151], v216 offset:17408
	ds_read_b128 v[152:155], v216 offset:18432
	ds_read_b128 v[156:159], v216 offset:19456
	s_add_i32 m0, s92, 0x10000
	ds_read_b128 v[160:163], v216 offset:20480
	ds_read_b128 v[164:167], v216 offset:21504
	ds_read_b128 v[168:171], v216 offset:22528
	ds_read_b128 v[172:175], v216 offset:23552
	global_load_lds_dwordx4 v192, s[44:45]
	s_add_i32 m0, s92, 0x12000
	s_nop 0
	global_load_lds_dwordx4 v180, s[44:45]
	s_add_i32 m0, s92, 0x14000
	s_nop 0
	global_load_lds_dwordx4 v192, s[76:77]
	s_add_i32 m0, s92, 0x16000
	s_nop 0
	global_load_lds_dwordx4 v180, s[76:77]
	s_waitcnt vmcnt(4)
	s_waitcnt lgkmcnt(0)
	s_barrier
	v_mfma_f32_16x16x32_bf16 v[60:63], v[128:131], v[144:147], 0
	v_mfma_f32_16x16x32_bf16 v[52:55], v[136:139], v[144:147], 0
	v_mfma_f32_16x16x32_bf16 v[44:47], v[128:131], v[152:155], 0
	v_mfma_f32_16x16x32_bf16 v[36:39], v[136:139], v[152:155], 0
	v_mfma_f32_16x16x32_bf16 v[28:31], v[128:131], v[160:163], 0
	v_mfma_f32_16x16x32_bf16 v[20:23], v[136:139], v[160:163], 0
	v_mfma_f32_16x16x32_bf16 v[12:15], v[128:131], v[168:171], 0
	v_mfma_f32_16x16x32_bf16 v[4:7], v[136:139], v[168:171], 0
	v_mfma_f32_16x16x32_bf16 v[60:63], v[132:135], v[148:151], v[60:63]
	v_mfma_f32_16x16x32_bf16 v[52:55], v[140:143], v[148:151], v[52:55]
	v_mfma_f32_16x16x32_bf16 v[44:47], v[132:135], v[156:159], v[44:47]
	v_mfma_f32_16x16x32_bf16 v[36:39], v[140:143], v[156:159], v[36:39]
	v_mfma_f32_16x16x32_bf16 v[28:31], v[132:135], v[164:167], v[28:31]
	v_mfma_f32_16x16x32_bf16 v[20:23], v[140:143], v[164:167], v[20:23]
	v_mfma_f32_16x16x32_bf16 v[12:15], v[132:135], v[172:175], v[12:15]
	v_mfma_f32_16x16x32_bf16 v[4:7], v[140:143], v[172:175], v[4:7]
	v_mfma_f32_16x16x32_bf16 v[56:59], v[188:191], v[144:147], 0
	v_mfma_f32_16x16x32_bf16 v[48:51], v[200:203], v[144:147], 0
	v_mfma_f32_16x16x32_bf16 v[40:43], v[188:191], v[152:155], 0
	v_mfma_f32_16x16x32_bf16 v[32:35], v[200:203], v[152:155], 0
	v_mfma_f32_16x16x32_bf16 v[24:27], v[188:191], v[160:163], 0
	v_mfma_f32_16x16x32_bf16 v[16:19], v[200:203], v[160:163], 0
	v_mfma_f32_16x16x32_bf16 v[8:11], v[188:191], v[168:171], 0
	v_mfma_f32_16x16x32_bf16 v[0:3], v[200:203], v[168:171], 0
	v_mfma_f32_16x16x32_bf16 v[56:59], v[196:199], v[148:151], v[56:59]
	v_mfma_f32_16x16x32_bf16 v[48:51], v[218:221], v[148:151], v[48:51]
	v_mfma_f32_16x16x32_bf16 v[40:43], v[196:199], v[156:159], v[40:43]
	v_mfma_f32_16x16x32_bf16 v[32:35], v[218:221], v[156:159], v[32:35]
	v_mfma_f32_16x16x32_bf16 v[24:27], v[196:199], v[164:167], v[24:27]
	v_mfma_f32_16x16x32_bf16 v[16:19], v[218:221], v[164:167], v[16:19]
	v_mfma_f32_16x16x32_bf16 v[8:11], v[196:199], v[172:175], v[8:11]
	v_mfma_f32_16x16x32_bf16 v[0:3], v[218:221], v[172:175], v[0:3]
	s_barrier
; #define PG8_STAGE(bufoff, gbase, voff) do { _Pragma("unroll") for (int _i = 0; _i < 2; ++_i) \
;         __builtin_amdgcn_global_load_lds((const unsigned*)((const char*)(gbase) + (voff)[_i]), (LAS unsigned*)(lds + (bufoff) + ldsw + _i * 8192), 16, 0, 0); } while (0)
; #define PG8_LDA(dst, b, h) do { _Pragma("unroll") for (int m = 0; m < 4; ++m) _Pragma("unroll") for (int k = 0; k < 2; ++k) dst[m][k] = *(const LAS bf16x8*)(lds + PG8_SA(b, h) + aoff + m * 2048 + k * 1024); } while (0)
; #define PG8_WAIT_V(n) asm volatile("s_waitcnt vmcnt(" #n ")" ::: "memory")
; #define PG8_WAIT_L(n) asm volatile("s_waitcnt lgkmcnt(" #n ")" ::: "memory")
; template <class Prog>
; __device__ __forceinline__ void gemm_phase(LAS unsigned char* lds, const int K, const Prog& S) {
;     ...
;         for (int t = 0; t < nt; t += 2) {
;             const bool last = (t == nt - 2);
;             const char* a1 = cA + (size_t)(t + 1) * kstep;
;             const char* a2 = last ? nA : cA + (size_t)(t + 2) * kstep; const char* b2 = last ? nB : cB + (size_t)(t + 2) * kstep;
;             const char* a3 = a2 + kstep; const char* b3 = b2 + kstep;
;             PG8_LDB(B0, 0, 0); PG8_SCHED; PG8_LDA(At, 0, 0); PG8_STAGE(PG8_SA(1, 1), a1 + hstep, voffA);
;             PG8_WAIT_L(8); PG8_BAR; PG8_WAIT_L(0); PG8_MMA(0, 0, At, B0); PG8_BAR; PG8_SCHED;
;             PG8_LDB(B1, 0, 1); PG8_STAGE(PG8_SB(0, 0), b2, voffB);
;             PG8_BAR; PG8_WAIT_L(0); PG8_MMA(0, 1, At, B1); PG8_BAR;
;             PG8_LDA(At, 0, 1); PG8_STAGE(PG8_SA(0, 0), a2, voffA);
;             PG8_BAR; PG8_WAIT_L(0); PG8_MMA(1, 0, At, B0); PG8_BAR; PG8_SCHED;
;             PG8_STAGE(PG8_SB(0, 1), b2 + hstep, voffB);
;             PG8_WAIT_V(6); PG8_BAR; PG8_MMA(1, 1, At, B1); PG8_BAR;
;             PG8_LDB(B0, 1, 0); PG8_SCHED; PG8_LDA(At, 1, 0); PG8_STAGE(PG8_SA(0, 1), a2 + hstep, voffA);
;             PG8_WAIT_L(8); PG8_BAR; PG8_WAIT_L(0); PG8_MMA(0, 0, At, B0); PG8_BAR; PG8_SCHED;
;             PG8_LDB(B1, 1, 1); PG8_STAGE(PG8_SB(1, 0), b3, voffB);
;             PG8_BAR; PG8_WAIT_L(0); PG8_MMA(0, 1, At, B1); PG8_BAR;
;             PG8_LDA(At, 1, 1); PG8_STAGE(PG8_SA(1, 0), a3, voffA);
;             PG8_BAR; PG8_WAIT_L(0); PG8_MMA(1, 0, At, B0); PG8_BAR; PG8_SCHED;
;             PG8_STAGE(PG8_SB(1, 1), b3 + hstep, voffB);
;             PG8_WAIT_V(6); PG8_BAR; PG8_MMA(1, 1, At, B1); PG8_BAR;
	ds_read_b128 v[128:131], v244 offset:32768
	ds_read_b128 v[132:135], v244 offset:33792
	ds_read_b128 v[136:139], v244 offset:34816
	ds_read_b128 v[140:143], v244 offset:35840
	s_mov_b32 m0, s92
	ds_read_b128 v[188:191], v244 offset:49152
	ds_read_b128 v[196:199], v244 offset:50176
	ds_read_b128 v[200:203], v244 offset:51200
	ds_read_b128 v[218:221], v244 offset:52224
	global_load_lds_dwordx4 v176, s[46:47]
	s_add_i32 m0, s92, 0x2000
	ds_read_b128 v[144:147], v216 offset:32768
	ds_read_b128 v[148:151], v216 offset:33792
	ds_read_b128 v[152:155], v216 offset:34816
	ds_read_b128 v[156:159], v216 offset:35840
	global_load_lds_dwordx4 v178, s[46:47]
	s_add_i32 m0, s92, 0x4000
	ds_read_b128 v[160:163], v216 offset:36864
	ds_read_b128 v[164:167], v216 offset:37888
	ds_read_b128 v[168:171], v216 offset:38912
	ds_read_b128 v[172:175], v216 offset:39936
	global_load_lds_dwordx4 v176, s[98:99]
	s_add_i32 m0, s92, 0x6000
	s_nop 0
	global_load_lds_dwordx4 v178, s[98:99]
	s_waitcnt lgkmcnt(0)
	s_barrier
	v_mfma_f32_16x16x32_bf16 v[124:127], v[128:131], v[144:147], v[124:127]
	v_mfma_f32_16x16x32_bf16 v[116:119], v[136:139], v[144:147], v[116:119]
	v_mfma_f32_16x16x32_bf16 v[108:111], v[128:131], v[152:155], v[108:111]
	v_mfma_f32_16x16x32_bf16 v[100:103], v[136:139], v[152:155], v[100:103]
	v_mfma_f32_16x16x32_bf16 v[92:95], v[128:131], v[160:163], v[92:95]
	v_mfma_f32_16x16x32_bf16 v[84:87], v[136:139], v[160:163], v[84:87]
	v_mfma_f32_16x16x32_bf16 v[76:79], v[128:131], v[168:171], v[76:79]
	v_mfma_f32_16x16x32_bf16 v[68:71], v[136:139], v[168:171], v[68:71]
	v_mfma_f32_16x16x32_bf16 v[124:127], v[132:135], v[148:151], v[124:127]
	v_mfma_f32_16x16x32_bf16 v[116:119], v[140:143], v[148:151], v[116:119]
	v_mfma_f32_16x16x32_bf16 v[108:111], v[132:135], v[156:159], v[108:111]
	v_mfma_f32_16x16x32_bf16 v[100:103], v[140:143], v[156:159], v[100:103]
	v_mfma_f32_16x16x32_bf16 v[92:95], v[132:135], v[164:167], v[92:95]
	v_mfma_f32_16x16x32_bf16 v[84:87], v[140:143], v[164:167], v[84:87]
	v_mfma_f32_16x16x32_bf16 v[76:79], v[132:135], v[172:175], v[76:79]
	v_mfma_f32_16x16x32_bf16 v[68:71], v[140:143], v[172:175], v[68:71]
	v_mfma_f32_16x16x32_bf16 v[120:123], v[188:191], v[144:147], v[120:123]
	v_mfma_f32_16x16x32_bf16 v[112:115], v[200:203], v[144:147], v[112:115]
	v_mfma_f32_16x16x32_bf16 v[104:107], v[188:191], v[152:155], v[104:107]
	v_mfma_f32_16x16x32_bf16 v[96:99], v[200:203], v[152:155], v[96:99]
	v_mfma_f32_16x16x32_bf16 v[88:91], v[188:191], v[160:163], v[88:91]
	v_mfma_f32_16x16x32_bf16 v[80:83], v[200:203], v[160:163], v[80:83]
	v_mfma_f32_16x16x32_bf16 v[72:75], v[188:191], v[168:171], v[72:75]
	v_mfma_f32_16x16x32_bf16 v[64:67], v[200:203], v[168:171], v[64:67]
	v_mfma_f32_16x16x32_bf16 v[120:123], v[196:199], v[148:151], v[120:123]
	v_mfma_f32_16x16x32_bf16 v[112:115], v[218:221], v[148:151], v[112:115]
	v_mfma_f32_16x16x32_bf16 v[104:107], v[196:199], v[156:159], v[104:107]
	v_mfma_f32_16x16x32_bf16 v[96:99], v[218:221], v[156:159], v[96:99]
	v_mfma_f32_16x16x32_bf16 v[88:91], v[196:199], v[164:167], v[88:91]
	v_mfma_f32_16x16x32_bf16 v[80:83], v[218:221], v[164:167], v[80:83]
	v_mfma_f32_16x16x32_bf16 v[72:75], v[196:199], v[172:175], v[72:75]
	v_mfma_f32_16x16x32_bf16 v[64:67], v[218:221], v[172:175], v[64:67]
	s_add_u32 s76, s44, 0x80
	s_addc_u32 s77, s45, 0
	s_add_u32 s98, s44, 0x80080
	s_addc_u32 s99, s45, 0
	s_add_i32 s69, s69, 2
	s_add_u32 s40, s40, 0x100
	s_addc_u32 s41, s41, 0
	s_add_u32 s9, s9, 0x100
	s_addc_u32 s15, s15, 0
	s_add_u32 s44, s40, 0xfff80080
	s_addc_u32 s45, s41, -1
	s_cmp_eq_u32 s69, 28
	s_cselect_b32 s47, s5, s45
	s_cselect_b32 s46, s4, s44
	s_cselect_b32 s45, s13, s15
	s_cselect_b32 s44, s12, s9
	s_add_u32 s100, s40, 0xfff80000
	s_addc_u32 s101, s41, -1
	s_barrier
	ds_read_b128 v[144:147], v216 offset:49152
	ds_read_b128 v[148:151], v216 offset:50176
	ds_read_b128 v[152:155], v216 offset:51200
	ds_read_b128 v[156:159], v216 offset:52224
	s_add_i32 m0, s92, 0x18000
	ds_read_b128 v[160:163], v216 offset:53248
	ds_read_b128 v[164:167], v216 offset:54272
	ds_read_b128 v[168:171], v216 offset:55296
	ds_read_b128 v[172:175], v216 offset:56320
	global_load_lds_dwordx4 v192, s[76:77]
	s_add_i32 m0, s92, 0x1a000
	s_nop 0
	global_load_lds_dwordx4 v180, s[76:77]
	s_add_i32 m0, s92, 0x1c000
	s_nop 0
	global_load_lds_dwordx4 v192, s[98:99]
	s_add_i32 m0, s92, 0x1e000
	s_nop 0
	global_load_lds_dwordx4 v180, s[98:99]
	s_waitcnt vmcnt(4)
	s_waitcnt lgkmcnt(0)
	s_barrier
	v_mfma_f32_16x16x32_bf16 v[60:63], v[128:131], v[144:147], v[60:63]
	v_mfma_f32_16x16x32_bf16 v[52:55], v[136:139], v[144:147], v[52:55]
	v_mfma_f32_16x16x32_bf16 v[44:47], v[128:131], v[152:155], v[44:47]
	v_mfma_f32_16x16x32_bf16 v[36:39], v[136:139], v[152:155], v[36:39]
	v_mfma_f32_16x16x32_bf16 v[28:31], v[128:131], v[160:163], v[28:31]
	v_mfma_f32_16x16x32_bf16 v[20:23], v[136:139], v[160:163], v[20:23]
	v_mfma_f32_16x16x32_bf16 v[12:15], v[128:131], v[168:171], v[12:15]
	v_mfma_f32_16x16x32_bf16 v[4:7], v[136:139], v[168:171], v[4:7]
	v_mfma_f32_16x16x32_bf16 v[60:63], v[132:135], v[148:151], v[60:63]
	v_mfma_f32_16x16x32_bf16 v[52:55], v[140:143], v[148:151], v[52:55]
	v_mfma_f32_16x16x32_bf16 v[44:47], v[132:135], v[156:159], v[44:47]
	v_mfma_f32_16x16x32_bf16 v[36:39], v[140:143], v[156:159], v[36:39]
	v_mfma_f32_16x16x32_bf16 v[28:31], v[132:135], v[164:167], v[28:31]
	v_mfma_f32_16x16x32_bf16 v[20:23], v[140:143], v[164:167], v[20:23]
	v_mfma_f32_16x16x32_bf16 v[12:15], v[132:135], v[172:175], v[12:15]
	v_mfma_f32_16x16x32_bf16 v[4:7], v[140:143], v[172:175], v[4:7]
	v_mfma_f32_16x16x32_bf16 v[56:59], v[188:191], v[144:147], v[56:59]
	v_mfma_f32_16x16x32_bf16 v[48:51], v[200:203], v[144:147], v[48:51]
	v_mfma_f32_16x16x32_bf16 v[40:43], v[188:191], v[152:155], v[40:43]
	v_mfma_f32_16x16x32_bf16 v[32:35], v[200:203], v[152:155], v[32:35]
	v_mfma_f32_16x16x32_bf16 v[24:27], v[188:191], v[160:163], v[24:27]
	v_mfma_f32_16x16x32_bf16 v[16:19], v[200:203], v[160:163], v[16:19]
	v_mfma_f32_16x16x32_bf16 v[8:11], v[188:191], v[168:171], v[8:11]
	v_mfma_f32_16x16x32_bf16 v[0:3], v[200:203], v[168:171], v[0:3]
	v_mfma_f32_16x16x32_bf16 v[56:59], v[196:199], v[148:151], v[56:59]
	v_mfma_f32_16x16x32_bf16 v[48:51], v[218:221], v[148:151], v[48:51]
	v_mfma_f32_16x16x32_bf16 v[40:43], v[196:199], v[156:159], v[40:43]
	v_mfma_f32_16x16x32_bf16 v[32:35], v[218:221], v[156:159], v[32:35]
	v_mfma_f32_16x16x32_bf16 v[24:27], v[196:199], v[164:167], v[24:27]
	v_mfma_f32_16x16x32_bf16 v[16:19], v[218:221], v[164:167], v[16:19]
	v_mfma_f32_16x16x32_bf16 v[8:11], v[196:199], v[172:175], v[8:11]
	v_mfma_f32_16x16x32_bf16 v[0:3], v[218:221], v[172:175], v[0:3]
	s_cmp_gt_u32 s69, 29
	s_barrier
	.p2align 6
; #define PG8_STAGE(bufoff, gbase, voff) do { _Pragma("unroll") for (int _i = 0; _i < 2; ++_i) \
;         __builtin_amdgcn_global_load_lds((const unsigned*)((const char*)(gbase) + (voff)[_i]), (LAS unsigned*)(lds + (bufoff) + ldsw + _i * 8192), 16, 0, 0); } while (0)
; #define PG8_LDA(dst, b, h) do { _Pragma("unroll") for (int m = 0; m < 4; ++m) _Pragma("unroll") for (int k = 0; k < 2; ++k) dst[m][k] = *(const LAS bf16x8*)(lds + PG8_SA(b, h) + aoff + m * 2048 + k * 1024); } while (0)
; #define PG8_WAIT_V(n) asm volatile("s_waitcnt vmcnt(" #n ")" ::: "memory")
; #define PG8_WAIT_L(n) asm volatile("s_waitcnt lgkmcnt(" #n ")" ::: "memory")
; template <class Prog>
; __device__ __forceinline__ void gemm_phase(LAS unsigned char* lds, const int K, const Prog& S) {
;     ...
;         for (int t = 0; t < nt; t += 2) {
;             const bool last = (t == nt - 2);
;             const char* a1 = cA + (size_t)(t + 1) * kstep;
;             const char* a2 = last ? nA : cA + (size_t)(t + 2) * kstep; const char* b2 = last ? nB : cB + (size_t)(t + 2) * kstep;
;             const char* a3 = a2 + kstep; const char* b3 = b2 + kstep;
;             PG8_LDB(B0, 0, 0); PG8_SCHED; PG8_LDA(At, 0, 0); PG8_STAGE(PG8_SA(1, 1), a1 + hstep, voffA);
;             PG8_WAIT_L(8); PG8_BAR; PG8_WAIT_L(0); PG8_MMA(0, 0, At, B0); PG8_BAR; PG8_SCHED;
;             PG8_LDB(B1, 0, 1); PG8_STAGE(PG8_SB(0, 0), b2, voffB);
;             PG8_BAR; PG8_WAIT_L(0); PG8_MMA(0, 1, At, B1); PG8_BAR;
;             PG8_LDA(At, 0, 1); PG8_STAGE(PG8_SA(0, 0), a2, voffA);
;             PG8_BAR; PG8_WAIT_L(0); PG8_MMA(1, 0, At, B0); PG8_BAR; PG8_SCHED;
;             PG8_STAGE(PG8_SB(0, 1), b2 + hstep, voffB);
;             PG8_WAIT_V(6); PG8_BAR; PG8_MMA(1, 1, At, B1); PG8_BAR;
;             PG8_LDB(B0, 1, 0); PG8_SCHED; PG8_LDA(At, 1, 0); PG8_STAGE(PG8_SA(0, 1), a2 + hstep, voffA);
;             PG8_WAIT_L(8); PG8_BAR; PG8_WAIT_L(0); PG8_MMA(0, 0, At, B0); PG8_BAR; PG8_SCHED;
;             PG8_LDB(B1, 1, 1); PG8_STAGE(PG8_SB(1, 0), b3, voffB);
;             PG8_BAR; PG8_WAIT_L(0); PG8_MMA(0, 1, At, B1); PG8_BAR;
;             PG8_LDA(At, 1, 1); PG8_STAGE(PG8_SA(1, 0), a3, voffA);
;             PG8_BAR; PG8_WAIT_L(0); PG8_MMA(1, 0, At, B0); PG8_BAR; PG8_SCHED;
;             PG8_STAGE(PG8_SB(1, 1), b3 + hstep, voffB);
;             PG8_WAIT_V(6); PG8_BAR; PG8_MMA(1, 1, At, B1); PG8_BAR;
.LBB0_101:
	ds_read_b128 v[128:131], v244
	ds_read_b128 v[132:135], v244 offset:1024
	ds_read_b128 v[136:139], v244 offset:2048
	ds_read_b128 v[140:143], v244 offset:3072
	s_add_i32 m0, s92, 0x8000
	ds_read_b128 v[188:191], v244 offset:16384
	ds_read_b128 v[196:199], v244 offset:17408
	ds_read_b128 v[200:203], v244 offset:18432
	ds_read_b128 v[218:221], v244 offset:19456
	global_load_lds_dwordx4 v184, s[100:101]
	s_add_i32 m0, s92, 0xa000
	ds_read_b128 v[144:147], v216
	ds_read_b128 v[148:151], v216 offset:1024
	ds_read_b128 v[152:155], v216 offset:2048
	ds_read_b128 v[156:159], v216 offset:3072
	global_load_lds_dwordx4 v186, s[100:101]
	s_add_i32 m0, s92, 0xc000
	ds_read_b128 v[160:163], v216 offset:4096
	ds_read_b128 v[164:167], v216 offset:5120
	ds_read_b128 v[168:171], v216 offset:6144
	ds_read_b128 v[172:175], v216 offset:7168
	global_load_lds_dwordx4 v184, s[40:41]
	s_add_i32 m0, s92, 0xe000
	s_nop 0
	global_load_lds_dwordx4 v186, s[40:41]
	s_waitcnt lgkmcnt(0)
	s_barrier
	v_mfma_f32_16x16x32_bf16 v[124:127], v[128:131], v[144:147], v[124:127]
	v_mfma_f32_16x16x32_bf16 v[116:119], v[136:139], v[144:147], v[116:119]
	v_mfma_f32_16x16x32_bf16 v[108:111], v[128:131], v[152:155], v[108:111]
	v_mfma_f32_16x16x32_bf16 v[100:103], v[136:139], v[152:155], v[100:103]
	v_mfma_f32_16x16x32_bf16 v[92:95], v[128:131], v[160:163], v[92:95]
	v_mfma_f32_16x16x32_bf16 v[84:87], v[136:139], v[160:163], v[84:87]
	v_mfma_f32_16x16x32_bf16 v[76:79], v[128:131], v[168:171], v[76:79]
	v_mfma_f32_16x16x32_bf16 v[68:71], v[136:139], v[168:171], v[68:71]
	v_mfma_f32_16x16x32_bf16 v[124:127], v[132:135], v[148:151], v[124:127]
	v_mfma_f32_16x16x32_bf16 v[116:119], v[140:143], v[148:151], v[116:119]
	v_mfma_f32_16x16x32_bf16 v[108:111], v[132:135], v[156:159], v[108:111]
	v_mfma_f32_16x16x32_bf16 v[100:103], v[140:143], v[156:159], v[100:103]
	v_mfma_f32_16x16x32_bf16 v[92:95], v[132:135], v[164:167], v[92:95]
	v_mfma_f32_16x16x32_bf16 v[84:87], v[140:143], v[164:167], v[84:87]
	v_mfma_f32_16x16x32_bf16 v[76:79], v[132:135], v[172:175], v[76:79]
	v_mfma_f32_16x16x32_bf16 v[68:71], v[140:143], v[172:175], v[68:71]
	v_mfma_f32_16x16x32_bf16 v[120:123], v[188:191], v[144:147], v[120:123]
	v_mfma_f32_16x16x32_bf16 v[112:115], v[200:203], v[144:147], v[112:115]
	v_mfma_f32_16x16x32_bf16 v[104:107], v[188:191], v[152:155], v[104:107]
	v_mfma_f32_16x16x32_bf16 v[96:99], v[200:203], v[152:155], v[96:99]
	v_mfma_f32_16x16x32_bf16 v[88:91], v[188:191], v[160:163], v[88:91]
	v_mfma_f32_16x16x32_bf16 v[80:83], v[200:203], v[160:163], v[80:83]
	v_mfma_f32_16x16x32_bf16 v[72:75], v[188:191], v[168:171], v[72:75]
	v_mfma_f32_16x16x32_bf16 v[64:67], v[200:203], v[168:171], v[64:67]
	v_mfma_f32_16x16x32_bf16 v[120:123], v[196:199], v[148:151], v[120:123]
	v_mfma_f32_16x16x32_bf16 v[112:115], v[218:221], v[148:151], v[112:115]
	v_mfma_f32_16x16x32_bf16 v[104:107], v[196:199], v[156:159], v[104:107]
	v_mfma_f32_16x16x32_bf16 v[96:99], v[218:221], v[156:159], v[96:99]
	v_mfma_f32_16x16x32_bf16 v[88:91], v[196:199], v[164:167], v[88:91]
	v_mfma_f32_16x16x32_bf16 v[80:83], v[218:221], v[164:167], v[80:83]
	v_mfma_f32_16x16x32_bf16 v[72:75], v[196:199], v[172:175], v[72:75]
	v_mfma_f32_16x16x32_bf16 v[64:67], v[218:221], v[172:175], v[64:67]
	s_add_u32 s76, s44, 0x80000
	s_addc_u32 s77, s45, 0
	s_add_u32 s98, s46, 0x80000
	s_addc_u32 s99, s47, 0
	s_barrier
	ds_read_b128 v[144:147], v216 offset:16384
	ds_read_b128 v[148:151], v216 offset:17408
	ds_read_b128 v[152:155], v216 offset:18432
	ds_read_b128 v[156:159], v216 offset:19456
	s_add_i32 m0, s92, 0x10000
	ds_read_b128 v[160:163], v216 offset:20480
	ds_read_b128 v[164:167], v216 offset:21504
	ds_read_b128 v[168:171], v216 offset:22528
	ds_read_b128 v[172:175], v216 offset:23552
	global_load_lds_dwordx4 v192, s[44:45]
	s_add_i32 m0, s92, 0x12000
	s_nop 0
	global_load_lds_dwordx4 v180, s[44:45]
	s_add_i32 m0, s92, 0x14000
	s_nop 0
	global_load_lds_dwordx4 v192, s[76:77]
	s_add_i32 m0, s92, 0x16000
	s_nop 0
	global_load_lds_dwordx4 v180, s[76:77]
	s_waitcnt vmcnt(4)
	s_waitcnt lgkmcnt(0)
	s_barrier
	v_mfma_f32_16x16x32_bf16 v[60:63], v[128:131], v[144:147], v[60:63]
	v_mfma_f32_16x16x32_bf16 v[52:55], v[136:139], v[144:147], v[52:55]
	v_mfma_f32_16x16x32_bf16 v[44:47], v[128:131], v[152:155], v[44:47]
	v_mfma_f32_16x16x32_bf16 v[36:39], v[136:139], v[152:155], v[36:39]
	v_mfma_f32_16x16x32_bf16 v[28:31], v[128:131], v[160:163], v[28:31]
	v_mfma_f32_16x16x32_bf16 v[20:23], v[136:139], v[160:163], v[20:23]
	v_mfma_f32_16x16x32_bf16 v[12:15], v[128:131], v[168:171], v[12:15]
	v_mfma_f32_16x16x32_bf16 v[4:7], v[136:139], v[168:171], v[4:7]
	v_mfma_f32_16x16x32_bf16 v[60:63], v[132:135], v[148:151], v[60:63]
	v_mfma_f32_16x16x32_bf16 v[52:55], v[140:143], v[148:151], v[52:55]
	v_mfma_f32_16x16x32_bf16 v[44:47], v[132:135], v[156:159], v[44:47]
	v_mfma_f32_16x16x32_bf16 v[36:39], v[140:143], v[156:159], v[36:39]
	v_mfma_f32_16x16x32_bf16 v[28:31], v[132:135], v[164:167], v[28:31]
	v_mfma_f32_16x16x32_bf16 v[20:23], v[140:143], v[164:167], v[20:23]
	v_mfma_f32_16x16x32_bf16 v[12:15], v[132:135], v[172:175], v[12:15]
	v_mfma_f32_16x16x32_bf16 v[4:7], v[140:143], v[172:175], v[4:7]
	v_mfma_f32_16x16x32_bf16 v[56:59], v[188:191], v[144:147], v[56:59]
	v_mfma_f32_16x16x32_bf16 v[48:51], v[200:203], v[144:147], v[48:51]
	v_mfma_f32_16x16x32_bf16 v[40:43], v[188:191], v[152:155], v[40:43]
	v_mfma_f32_16x16x32_bf16 v[32:35], v[200:203], v[152:155], v[32:35]
	v_mfma_f32_16x16x32_bf16 v[24:27], v[188:191], v[160:163], v[24:27]
	v_mfma_f32_16x16x32_bf16 v[16:19], v[200:203], v[160:163], v[16:19]
	v_mfma_f32_16x16x32_bf16 v[8:11], v[188:191], v[168:171], v[8:11]
	v_mfma_f32_16x16x32_bf16 v[0:3], v[200:203], v[168:171], v[0:3]
	v_mfma_f32_16x16x32_bf16 v[56:59], v[196:199], v[148:151], v[56:59]
	v_mfma_f32_16x16x32_bf16 v[48:51], v[218:221], v[148:151], v[48:51]
	v_mfma_f32_16x16x32_bf16 v[40:43], v[196:199], v[156:159], v[40:43]
	v_mfma_f32_16x16x32_bf16 v[32:35], v[218:221], v[156:159], v[32:35]
	v_mfma_f32_16x16x32_bf16 v[24:27], v[196:199], v[164:167], v[24:27]
	v_mfma_f32_16x16x32_bf16 v[16:19], v[218:221], v[164:167], v[16:19]
	v_mfma_f32_16x16x32_bf16 v[8:11], v[196:199], v[172:175], v[8:11]
	v_mfma_f32_16x16x32_bf16 v[0:3], v[218:221], v[172:175], v[0:3]
	s_barrier
; #define PG8_STAGE(bufoff, gbase, voff) do { _Pragma("unroll") for (int _i = 0; _i < 2; ++_i) \
;         __builtin_amdgcn_global_load_lds((const unsigned*)((const char*)(gbase) + (voff)[_i]), (LAS unsigned*)(lds + (bufoff) + ldsw + _i * 8192), 16, 0, 0); } while (0)
; #define PG8_WAIT_V(n) asm volatile("s_waitcnt vmcnt(" #n ")" ::: "memory")
; template <class Prog>
; __device__ __forceinline__ void gemm_phase(LAS unsigned char* lds, const int K, const Prog& S) {
;     ...
;         for (int t = 0; t < nt; t += 2) {
;             const bool last = (t == nt - 2);
;             const char* a1 = cA + (size_t)(t + 1) * kstep;
;             const char* a2 = last ? nA : cA + (size_t)(t + 2) * kstep; const char* b2 = last ? nB : cB + (size_t)(t + 2) * kstep;
;             const char* a3 = a2 + kstep; const char* b3 = b2 + kstep;
;             PG8_LDB(B0, 0, 0); PG8_SCHED; PG8_LDA(At, 0, 0); PG8_STAGE(PG8_SA(1, 1), a1 + hstep, voffA);
;             PG8_WAIT_L(8); PG8_BAR; PG8_WAIT_L(0); PG8_MMA(0, 0, At, B0); PG8_BAR; PG8_SCHED;
;             PG8_LDB(B1, 0, 1); PG8_STAGE(PG8_SB(0, 0), b2, voffB);
;             PG8_BAR; PG8_WAIT_L(0); PG8_MMA(0, 1, At, B1); PG8_BAR;
;             PG8_LDA(At, 0, 1); PG8_STAGE(PG8_SA(0, 0), a2, voffA);
;             PG8_BAR; PG8_WAIT_L(0); PG8_MMA(1, 0, At, B0); PG8_BAR; PG8_SCHED;
;             PG8_STAGE(PG8_SB(0, 1), b2 + hstep, voffB);
;             PG8_WAIT_V(6); PG8_BAR; PG8_MMA(1, 1, At, B1); PG8_BAR;
;             PG8_LDB(B0, 1, 0); PG8_SCHED; PG8_LDA(At, 1, 0); PG8_STAGE(PG8_SA(0, 1), a2 + hstep, voffA);
;             PG8_WAIT_L(8); PG8_BAR; PG8_WAIT_L(0); PG8_MMA(0, 0, At, B0); PG8_BAR; PG8_SCHED;
;             PG8_LDB(B1, 1, 1); PG8_STAGE(PG8_SB(1, 0), b3, voffB);
;             PG8_BAR; PG8_WAIT_L(0); PG8_MMA(0, 1, At, B1); PG8_BAR;
;             PG8_LDA(At, 1, 1); PG8_STAGE(PG8_SA(1, 0), a3, voffA);
;             PG8_BAR; PG8_WAIT_L(0); PG8_MMA(1, 0, At, B0); PG8_BAR; PG8_SCHED;
;             PG8_STAGE(PG8_SB(1, 1), b3 + hstep, voffB);
;             PG8_WAIT_V(6); PG8_BAR; PG8_MMA(1, 1, At, B1); PG8_BAR;
;     __device__ __forceinline__ void epi(f32x4 (&acc)[2][2][4][2], const pg8::Unit& u, int wr, int wc, int fr, int fq) const {
;     ...
;         const int pn = u.pn;
;         const int mode = (pn < 8) ? 1 : ((pn >= 12 && pn < 16) || (pn >= 20 && pn < 24) || (pn >= 30 && pn < 34)) ? 2 : (pn >= 34 ? 3 : 0);
	ds_read_b128 v[128:131], v244 offset:32768
	ds_read_b128 v[132:135], v244 offset:33792
	ds_read_b128 v[136:139], v244 offset:34816
	ds_read_b128 v[140:143], v244 offset:35840
	s_mov_b32 m0, s92
	ds_read_b128 v[188:191], v244 offset:49152
	ds_read_b128 v[196:199], v244 offset:50176
	ds_read_b128 v[200:203], v244 offset:51200
	ds_read_b128 v[218:221], v244 offset:52224
	global_load_lds_dwordx4 v176, s[46:47]
	s_add_i32 m0, s92, 0x2000
	ds_read_b128 v[144:147], v216 offset:32768
	ds_read_b128 v[148:151], v216 offset:33792
	ds_read_b128 v[152:155], v216 offset:34816
	ds_read_b128 v[156:159], v216 offset:35840
	global_load_lds_dwordx4 v178, s[46:47]
	s_add_i32 m0, s92, 0x4000
	ds_read_b128 v[160:163], v216 offset:36864
	ds_read_b128 v[164:167], v216 offset:37888
	ds_read_b128 v[168:171], v216 offset:38912
	ds_read_b128 v[172:175], v216 offset:39936
	global_load_lds_dwordx4 v176, s[98:99]
	s_add_i32 m0, s92, 0x6000
	s_nop 0
	global_load_lds_dwordx4 v178, s[98:99]
	s_waitcnt lgkmcnt(0)
	s_barrier
	v_mfma_f32_16x16x32_bf16 v[124:127], v[128:131], v[144:147], v[124:127]
	v_mfma_f32_16x16x32_bf16 v[116:119], v[136:139], v[144:147], v[116:119]
	v_mfma_f32_16x16x32_bf16 v[108:111], v[128:131], v[152:155], v[108:111]
	v_mfma_f32_16x16x32_bf16 v[100:103], v[136:139], v[152:155], v[100:103]
	v_mfma_f32_16x16x32_bf16 v[92:95], v[128:131], v[160:163], v[92:95]
	v_mfma_f32_16x16x32_bf16 v[84:87], v[136:139], v[160:163], v[84:87]
	v_mfma_f32_16x16x32_bf16 v[76:79], v[128:131], v[168:171], v[76:79]
	v_mfma_f32_16x16x32_bf16 v[68:71], v[136:139], v[168:171], v[68:71]
	v_mfma_f32_16x16x32_bf16 v[124:127], v[132:135], v[148:151], v[124:127]
	v_mfma_f32_16x16x32_bf16 v[116:119], v[140:143], v[148:151], v[116:119]
	v_mfma_f32_16x16x32_bf16 v[108:111], v[132:135], v[156:159], v[108:111]
	v_mfma_f32_16x16x32_bf16 v[100:103], v[140:143], v[156:159], v[100:103]
	v_mfma_f32_16x16x32_bf16 v[92:95], v[132:135], v[164:167], v[92:95]
	v_mfma_f32_16x16x32_bf16 v[84:87], v[140:143], v[164:167], v[84:87]
	v_mfma_f32_16x16x32_bf16 v[76:79], v[132:135], v[172:175], v[76:79]
	v_mfma_f32_16x16x32_bf16 v[68:71], v[140:143], v[172:175], v[68:71]
	v_mfma_f32_16x16x32_bf16 v[120:123], v[188:191], v[144:147], v[120:123]
	v_mfma_f32_16x16x32_bf16 v[112:115], v[200:203], v[144:147], v[112:115]
	v_mfma_f32_16x16x32_bf16 v[104:107], v[188:191], v[152:155], v[104:107]
	v_mfma_f32_16x16x32_bf16 v[96:99], v[200:203], v[152:155], v[96:99]
	v_mfma_f32_16x16x32_bf16 v[88:91], v[188:191], v[160:163], v[88:91]
	v_mfma_f32_16x16x32_bf16 v[80:83], v[200:203], v[160:163], v[80:83]
	v_mfma_f32_16x16x32_bf16 v[72:75], v[188:191], v[168:171], v[72:75]
	v_mfma_f32_16x16x32_bf16 v[64:67], v[200:203], v[168:171], v[64:67]
	v_mfma_f32_16x16x32_bf16 v[120:123], v[196:199], v[148:151], v[120:123]
	v_mfma_f32_16x16x32_bf16 v[112:115], v[218:221], v[148:151], v[112:115]
	v_mfma_f32_16x16x32_bf16 v[104:107], v[196:199], v[156:159], v[104:107]
	v_mfma_f32_16x16x32_bf16 v[96:99], v[218:221], v[156:159], v[96:99]
	v_mfma_f32_16x16x32_bf16 v[88:91], v[196:199], v[164:167], v[88:91]
	v_mfma_f32_16x16x32_bf16 v[80:83], v[218:221], v[164:167], v[80:83]
	v_mfma_f32_16x16x32_bf16 v[72:75], v[196:199], v[172:175], v[72:75]
	v_mfma_f32_16x16x32_bf16 v[64:67], v[218:221], v[172:175], v[64:67]
	s_add_u32 s76, s44, 0x80
	s_addc_u32 s77, s45, 0
	s_add_u32 s98, s44, 0x80080
	s_addc_u32 s99, s45, 0
	s_add_i32 s69, s69, 2
	s_add_u32 s40, s40, 0x100
	s_addc_u32 s41, s41, 0
	s_add_u32 s9, s9, 0x100
	s_addc_u32 s15, s15, 0
	s_add_u32 s44, s40, 0xfff80080
	s_addc_u32 s45, s41, -1
	s_cmp_eq_u32 s69, 28
	s_cselect_b32 s47, s5, s45
	s_cselect_b32 s46, s4, s44
	s_cselect_b32 s45, s13, s15
	s_cselect_b32 s44, s12, s9
	s_add_u32 s100, s40, 0xfff80000
	s_addc_u32 s101, s41, -1
	s_barrier
	ds_read_b128 v[144:147], v216 offset:49152
	ds_read_b128 v[148:151], v216 offset:50176
	ds_read_b128 v[152:155], v216 offset:51200
	ds_read_b128 v[156:159], v216 offset:52224
	s_add_i32 m0, s92, 0x18000
	ds_read_b128 v[160:163], v216 offset:53248
	ds_read_b128 v[164:167], v216 offset:54272
	ds_read_b128 v[168:171], v216 offset:55296
	ds_read_b128 v[172:175], v216 offset:56320
	global_load_lds_dwordx4 v192, s[76:77]
	s_add_i32 m0, s92, 0x1a000
	s_nop 0
	global_load_lds_dwordx4 v180, s[76:77]
	s_add_i32 m0, s92, 0x1c000
	s_nop 0
	global_load_lds_dwordx4 v192, s[98:99]
	s_add_i32 m0, s92, 0x1e000
	s_nop 0
	global_load_lds_dwordx4 v180, s[98:99]
	s_waitcnt vmcnt(4)
	s_waitcnt lgkmcnt(0)
	s_barrier
	v_mfma_f32_16x16x32_bf16 v[60:63], v[128:131], v[144:147], v[60:63]
	v_mfma_f32_16x16x32_bf16 v[52:55], v[136:139], v[144:147], v[52:55]
	v_mfma_f32_16x16x32_bf16 v[44:47], v[128:131], v[152:155], v[44:47]
	v_mfma_f32_16x16x32_bf16 v[36:39], v[136:139], v[152:155], v[36:39]
	v_mfma_f32_16x16x32_bf16 v[28:31], v[128:131], v[160:163], v[28:31]
	v_mfma_f32_16x16x32_bf16 v[20:23], v[136:139], v[160:163], v[20:23]
	v_mfma_f32_16x16x32_bf16 v[12:15], v[128:131], v[168:171], v[12:15]
	v_mfma_f32_16x16x32_bf16 v[4:7], v[136:139], v[168:171], v[4:7]
	v_mfma_f32_16x16x32_bf16 v[60:63], v[132:135], v[148:151], v[60:63]
	v_mfma_f32_16x16x32_bf16 v[52:55], v[140:143], v[148:151], v[52:55]
	v_mfma_f32_16x16x32_bf16 v[44:47], v[132:135], v[156:159], v[44:47]
	v_mfma_f32_16x16x32_bf16 v[36:39], v[140:143], v[156:159], v[36:39]
	v_mfma_f32_16x16x32_bf16 v[28:31], v[132:135], v[164:167], v[28:31]
	v_mfma_f32_16x16x32_bf16 v[20:23], v[140:143], v[164:167], v[20:23]
	v_mfma_f32_16x16x32_bf16 v[12:15], v[132:135], v[172:175], v[12:15]
	v_mfma_f32_16x16x32_bf16 v[4:7], v[140:143], v[172:175], v[4:7]
	v_mfma_f32_16x16x32_bf16 v[56:59], v[188:191], v[144:147], v[56:59]
	v_mfma_f32_16x16x32_bf16 v[48:51], v[200:203], v[144:147], v[48:51]
	v_mfma_f32_16x16x32_bf16 v[40:43], v[188:191], v[152:155], v[40:43]
	v_mfma_f32_16x16x32_bf16 v[32:35], v[200:203], v[152:155], v[32:35]
	v_mfma_f32_16x16x32_bf16 v[24:27], v[188:191], v[160:163], v[24:27]
	v_mfma_f32_16x16x32_bf16 v[16:19], v[200:203], v[160:163], v[16:19]
	v_mfma_f32_16x16x32_bf16 v[8:11], v[188:191], v[168:171], v[8:11]
	v_mfma_f32_16x16x32_bf16 v[0:3], v[200:203], v[168:171], v[0:3]
	v_mfma_f32_16x16x32_bf16 v[56:59], v[196:199], v[148:151], v[56:59]
	v_mfma_f32_16x16x32_bf16 v[48:51], v[218:221], v[148:151], v[48:51]
	v_mfma_f32_16x16x32_bf16 v[40:43], v[196:199], v[156:159], v[40:43]
	v_mfma_f32_16x16x32_bf16 v[32:35], v[218:221], v[156:159], v[32:35]
	v_mfma_f32_16x16x32_bf16 v[24:27], v[196:199], v[164:167], v[24:27]
	v_mfma_f32_16x16x32_bf16 v[16:19], v[218:221], v[164:167], v[16:19]
	v_mfma_f32_16x16x32_bf16 v[8:11], v[196:199], v[172:175], v[8:11]
	v_mfma_f32_16x16x32_bf16 v[0:3], v[218:221], v[172:175], v[0:3]
	s_cmp_gt_u32 s69, 29
	s_barrier
	s_cbranch_scc0 .LBB0_101
	s_cmp_lt_i32 s75, 8
	s_mov_b32 s9, 1
	s_cbranch_scc1 .LBB0_110
	s_sub_i32 s4, s75, 30
	s_cmp_lt_u32 s4, 4
	s_mov_b32 s9, 2
	s_cbranch_scc1 .LBB0_110
	s_and_b32 s9, s75, 0x7ffffffc
	s_cmp_lt_i32 s9, 20
	s_cbranch_scc1 .LBB0_106
	s_cmp_lg_u32 s9, 20
	s_cselect_b64 s[4:5], -1, 0
	s_cbranch_execz .LBB0_107
	s_branch .LBB0_108

; #define PG8_STAGE(bufoff, gbase, voff) do { _Pragma("unroll") for (int _i = 0; _i < 2; ++_i) \
;         __builtin_amdgcn_global_load_lds((const unsigned*)((const char*)(gbase) + (voff)[_i]), (LAS unsigned*)(lds + (bufoff) + ldsw + _i * 8192), 16, 0, 0); } while (0)
; #define PG8_LDA(dst, b, h) do { _Pragma("unroll") for (int m = 0; m < 4; ++m) _Pragma("unroll") for (int k = 0; k < 2; ++k) dst[m][k] = *(const LAS bf16x8*)(lds + PG8_SA(b, h) + aoff + m * 2048 + k * 1024); } while (0)
; template <class Prog>
; __device__ __forceinline__ void gemm_phase(LAS unsigned char* lds, const int K, const Prog& S) {
;     ...
;     for (;;) {
;         const bool has_next = S.next(ui + 1, nxt);
;         const char* nA = has_next ? nxt.a : cA; const char* nB = has_next ? nxt.b : cB;
;         for (int t = 0; t < nt; t += 2) {
;             const bool last = (t == nt - 2);
;             const char* a1 = cA + (size_t)(t + 1) * kstep;
;             const char* a2 = last ? nA : cA + (size_t)(t + 2) * kstep; const char* b2 = last ? nB : cB + (size_t)(t + 2) * kstep;
;             const char* a3 = a2 + kstep; const char* b3 = b2 + kstep;
;             PG8_LDB(B0, 0, 0); PG8_SCHED; PG8_LDA(At, 0, 0); PG8_STAGE(PG8_SA(1, 1), a1 + hstep, voffA);
;             PG8_WAIT_L(8); PG8_BAR; PG8_WAIT_L(0); PG8_MMA(0, 0, At, B0); PG8_BAR; PG8_SCHED;
;             PG8_LDB(B1, 0, 1); PG8_STAGE(PG8_SB(0, 0), b2, voffB);
;             PG8_BAR; PG8_WAIT_L(0); PG8_MMA(0, 1, At, B1); PG8_BAR;
;             PG8_LDA(At, 0, 1); PG8_STAGE(PG8_SA(0, 0), a2, voffA);
;             PG8_BAR; PG8_WAIT_L(0); PG8_MMA(1, 0, At, B0); PG8_BAR; PG8_SCHED;
;             PG8_STAGE(PG8_SB(0, 1), b2 + hstep, voffB);
;             PG8_WAIT_V(6); PG8_BAR; PG8_MMA(1, 1, At, B1); PG8_BAR;
;             PG8_LDB(B0, 1, 0); PG8_SCHED; PG8_LDA(At, 1, 0); PG8_STAGE(PG8_SA(0, 1), a2 + hstep, voffA);
;             PG8_WAIT_L(8); PG8_BAR; PG8_WAIT_L(0); PG8_MMA(0, 0, At, B0); PG8_BAR; PG8_SCHED;
;             PG8_LDB(B1, 1, 1); PG8_STAGE(PG8_SB(1, 0), b3, voffB);
;             PG8_BAR; PG8_WAIT_L(0); PG8_MMA(0, 1, At, B1); PG8_BAR;
;             PG8_LDA(At, 1, 1); PG8_STAGE(PG8_SA(1, 0), a3, voffA);
;             PG8_BAR; PG8_WAIT_L(0); PG8_MMA(1, 0, At, B0); PG8_BAR; PG8_SCHED;
;             PG8_STAGE(PG8_SB(1, 1), b3 + hstep, voffB);
;             PG8_WAIT_V(6); PG8_BAR; PG8_MMA(1, 1, At, B1); PG8_BAR;
.LBB0_399:
	s_add_u32 s44, s44, 0x40080
	s_addc_u32 s45, s45, 0
	s_add_u32 s41, s46, 0x100
	s_addc_u32 s43, s47, 0
	s_mov_b32 s55, -2
	v_add_u32_e32 v206, 0x10000, v245
	s_add_u32 s46, s44, 0xfffc0080
	s_addc_u32 s47, s45, -1
	s_cmp_eq_u32 s55, 12
	s_cselect_b32 s53, s7, s47
	s_cselect_b32 s52, s6, s46
	s_cselect_b32 s47, s9, s43
	s_cselect_b32 s46, s8, s41
	s_add_u32 s100, s44, 0xfffc0000
	s_addc_u32 s101, s45, -1
	.p2align 6
.LBB0_400:
	ds_read_b128 v[128:131], v206
	ds_read_b128 v[132:135], v206 offset:1024
	ds_read_b128 v[136:139], v206 offset:2048
	ds_read_b128 v[140:143], v206 offset:3072
	s_add_i32 m0, s74, 0x8000
	ds_read_b128 v[176:179], v206 offset:16384
	ds_read_b128 v[180:183], v206 offset:17408
	ds_read_b128 v[184:187], v206 offset:18432
	ds_read_b128 v[188:191], v206 offset:19456
	global_load_lds_dwordx4 v202, s[100:101]
	s_add_i32 m0, s74, 0xa000
	ds_read_b128 v[144:147], v247
	ds_read_b128 v[148:151], v247 offset:1024
	ds_read_b128 v[152:155], v247 offset:2048
	ds_read_b128 v[156:159], v247 offset:3072
	global_load_lds_dwordx4 v204, s[100:101]
	s_add_i32 m0, s74, 0xc000
	ds_read_b128 v[160:163], v247 offset:4096
	ds_read_b128 v[164:167], v247 offset:5120
	ds_read_b128 v[168:171], v247 offset:6144
	ds_read_b128 v[172:175], v247 offset:7168
	global_load_lds_dwordx4 v202, s[44:45]
	s_add_i32 m0, s74, 0xe000
	s_nop 0
	global_load_lds_dwordx4 v204, s[44:45]
	s_waitcnt lgkmcnt(0)
	s_barrier
	v_mfma_f32_16x16x32_bf16 v[124:127], v[128:131], v[144:147], v[124:127]
	v_mfma_f32_16x16x32_bf16 v[120:123], v[136:139], v[144:147], v[120:123]
	v_mfma_f32_16x16x32_bf16 v[116:119], v[128:131], v[152:155], v[116:119]
	v_mfma_f32_16x16x32_bf16 v[112:115], v[136:139], v[152:155], v[112:115]
	v_mfma_f32_16x16x32_bf16 v[108:111], v[128:131], v[160:163], v[108:111]
	v_mfma_f32_16x16x32_bf16 v[104:107], v[136:139], v[160:163], v[104:107]
	v_mfma_f32_16x16x32_bf16 v[100:103], v[128:131], v[168:171], v[100:103]
	v_mfma_f32_16x16x32_bf16 v[96:99], v[136:139], v[168:171], v[96:99]
	v_mfma_f32_16x16x32_bf16 v[124:127], v[132:135], v[148:151], v[124:127]
	v_mfma_f32_16x16x32_bf16 v[120:123], v[140:143], v[148:151], v[120:123]
	v_mfma_f32_16x16x32_bf16 v[116:119], v[132:135], v[156:159], v[116:119]
	v_mfma_f32_16x16x32_bf16 v[112:115], v[140:143], v[156:159], v[112:115]
	v_mfma_f32_16x16x32_bf16 v[108:111], v[132:135], v[164:167], v[108:111]
	v_mfma_f32_16x16x32_bf16 v[104:107], v[140:143], v[164:167], v[104:107]
	v_mfma_f32_16x16x32_bf16 v[100:103], v[132:135], v[172:175], v[100:103]
	v_mfma_f32_16x16x32_bf16 v[96:99], v[140:143], v[172:175], v[96:99]
	v_mfma_f32_16x16x32_bf16 v[92:95], v[176:179], v[144:147], v[92:95]
	v_mfma_f32_16x16x32_bf16 v[88:91], v[184:187], v[144:147], v[88:91]
	v_mfma_f32_16x16x32_bf16 v[84:87], v[176:179], v[152:155], v[84:87]
	v_mfma_f32_16x16x32_bf16 v[80:83], v[184:187], v[152:155], v[80:83]
	v_mfma_f32_16x16x32_bf16 v[76:79], v[176:179], v[160:163], v[76:79]
	v_mfma_f32_16x16x32_bf16 v[72:75], v[184:187], v[160:163], v[72:75]
	v_mfma_f32_16x16x32_bf16 v[68:71], v[176:179], v[168:171], v[68:71]
	v_mfma_f32_16x16x32_bf16 v[64:67], v[184:187], v[168:171], v[64:67]
	v_mfma_f32_16x16x32_bf16 v[92:95], v[180:183], v[148:151], v[92:95]
	v_mfma_f32_16x16x32_bf16 v[88:91], v[188:191], v[148:151], v[88:91]
	v_mfma_f32_16x16x32_bf16 v[84:87], v[180:183], v[156:159], v[84:87]
	v_mfma_f32_16x16x32_bf16 v[80:83], v[188:191], v[156:159], v[80:83]
	v_mfma_f32_16x16x32_bf16 v[76:79], v[180:183], v[164:167], v[76:79]
	v_mfma_f32_16x16x32_bf16 v[72:75], v[188:191], v[164:167], v[72:75]
	v_mfma_f32_16x16x32_bf16 v[68:71], v[180:183], v[172:175], v[68:71]
	v_mfma_f32_16x16x32_bf16 v[64:67], v[188:191], v[172:175], v[64:67]
	s_add_u32 s84, s46, 0x40000
	s_addc_u32 s85, s47, 0
	s_add_u32 s98, s52, 0x40000
	s_addc_u32 s99, s53, 0
	s_barrier
	ds_read_b128 v[144:147], v247 offset:16384
	ds_read_b128 v[148:151], v247 offset:17408
	ds_read_b128 v[152:155], v247 offset:18432
	ds_read_b128 v[156:159], v247 offset:19456
	s_add_i32 m0, s74, 0x10000
	ds_read_b128 v[160:163], v247 offset:20480
	ds_read_b128 v[164:167], v247 offset:21504
	ds_read_b128 v[168:171], v247 offset:22528
	ds_read_b128 v[172:175], v247 offset:23552
	global_load_lds_dwordx4 v192, s[46:47]
	s_add_i32 m0, s74, 0x12000
	s_nop 0
	global_load_lds_dwordx4 v200, s[46:47]
	s_add_i32 m0, s74, 0x14000
	s_nop 0
	global_load_lds_dwordx4 v192, s[84:85]
	s_add_i32 m0, s74, 0x16000
	s_nop 0
	global_load_lds_dwordx4 v200, s[84:85]
	s_waitcnt vmcnt(4)
	s_waitcnt lgkmcnt(0)
	s_barrier
	v_mfma_f32_16x16x32_bf16 v[60:63], v[128:131], v[144:147], v[60:63]
	v_mfma_f32_16x16x32_bf16 v[56:59], v[136:139], v[144:147], v[56:59]
	v_mfma_f32_16x16x32_bf16 v[52:55], v[128:131], v[152:155], v[52:55]
	v_mfma_f32_16x16x32_bf16 v[48:51], v[136:139], v[152:155], v[48:51]
	v_mfma_f32_16x16x32_bf16 v[44:47], v[128:131], v[160:163], v[44:47]
	v_mfma_f32_16x16x32_bf16 v[40:43], v[136:139], v[160:163], v[40:43]
	v_mfma_f32_16x16x32_bf16 v[36:39], v[128:131], v[168:171], v[36:39]
	v_mfma_f32_16x16x32_bf16 v[32:35], v[136:139], v[168:171], v[32:35]
	v_mfma_f32_16x16x32_bf16 v[60:63], v[132:135], v[148:151], v[60:63]
	v_mfma_f32_16x16x32_bf16 v[56:59], v[140:143], v[148:151], v[56:59]
	v_mfma_f32_16x16x32_bf16 v[52:55], v[132:135], v[156:159], v[52:55]
	v_mfma_f32_16x16x32_bf16 v[48:51], v[140:143], v[156:159], v[48:51]
	v_mfma_f32_16x16x32_bf16 v[44:47], v[132:135], v[164:167], v[44:47]
	v_mfma_f32_16x16x32_bf16 v[40:43], v[140:143], v[164:167], v[40:43]
	v_mfma_f32_16x16x32_bf16 v[36:39], v[132:135], v[172:175], v[36:39]
	v_mfma_f32_16x16x32_bf16 v[32:35], v[140:143], v[172:175], v[32:35]
	v_mfma_f32_16x16x32_bf16 v[28:31], v[176:179], v[144:147], v[28:31]
	v_mfma_f32_16x16x32_bf16 v[24:27], v[184:187], v[144:147], v[24:27]
	v_mfma_f32_16x16x32_bf16 v[20:23], v[176:179], v[152:155], v[20:23]
	v_mfma_f32_16x16x32_bf16 v[16:19], v[184:187], v[152:155], v[16:19]
	v_mfma_f32_16x16x32_bf16 v[12:15], v[176:179], v[160:163], v[12:15]
	v_mfma_f32_16x16x32_bf16 v[8:11], v[184:187], v[160:163], v[8:11]
	v_mfma_f32_16x16x32_bf16 v[4:7], v[176:179], v[168:171], v[4:7]
	v_mfma_f32_16x16x32_bf16 v[0:3], v[184:187], v[168:171], v[0:3]
	v_mfma_f32_16x16x32_bf16 v[28:31], v[180:183], v[148:151], v[28:31]
	v_mfma_f32_16x16x32_bf16 v[24:27], v[188:191], v[148:151], v[24:27]
	v_mfma_f32_16x16x32_bf16 v[20:23], v[180:183], v[156:159], v[20:23]
	v_mfma_f32_16x16x32_bf16 v[16:19], v[188:191], v[156:159], v[16:19]
	v_mfma_f32_16x16x32_bf16 v[12:15], v[180:183], v[164:167], v[12:15]
	v_mfma_f32_16x16x32_bf16 v[8:11], v[188:191], v[164:167], v[8:11]
	v_mfma_f32_16x16x32_bf16 v[4:7], v[180:183], v[172:175], v[4:7]
	v_mfma_f32_16x16x32_bf16 v[0:3], v[188:191], v[172:175], v[0:3]
	s_barrier
; #define PG8_STAGE(bufoff, gbase, voff) do { _Pragma("unroll") for (int _i = 0; _i < 2; ++_i) \
;         __builtin_amdgcn_global_load_lds((const unsigned*)((const char*)(gbase) + (voff)[_i]), (LAS unsigned*)(lds + (bufoff) + ldsw + _i * 8192), 16, 0, 0); } while (0)
; #define PG8_LDA(dst, b, h) do { _Pragma("unroll") for (int m = 0; m < 4; ++m) _Pragma("unroll") for (int k = 0; k < 2; ++k) dst[m][k] = *(const LAS bf16x8*)(lds + PG8_SA(b, h) + aoff + m * 2048 + k * 1024); } while (0)
; #define PG8_WAIT_V(n) asm volatile("s_waitcnt vmcnt(" #n ")" ::: "memory")
; #define PG8_WAIT_L(n) asm volatile("s_waitcnt lgkmcnt(" #n ")" ::: "memory")
; template <class Prog>
; __device__ __forceinline__ void gemm_phase(LAS unsigned char* lds, const int K, const Prog& S) {
;     ...
;         for (int t = 0; t < nt; t += 2) {
;             const bool last = (t == nt - 2);
;             const char* a1 = cA + (size_t)(t + 1) * kstep;
;             const char* a2 = last ? nA : cA + (size_t)(t + 2) * kstep; const char* b2 = last ? nB : cB + (size_t)(t + 2) * kstep;
;             const char* a3 = a2 + kstep; const char* b3 = b2 + kstep;
;             PG8_LDB(B0, 0, 0); PG8_SCHED; PG8_LDA(At, 0, 0); PG8_STAGE(PG8_SA(1, 1), a1 + hstep, voffA);
;             PG8_WAIT_L(8); PG8_BAR; PG8_WAIT_L(0); PG8_MMA(0, 0, At, B0); PG8_BAR; PG8_SCHED;
;             PG8_LDB(B1, 0, 1); PG8_STAGE(PG8_SB(0, 0), b2, voffB);
;             PG8_BAR; PG8_WAIT_L(0); PG8_MMA(0, 1, At, B1); PG8_BAR;
;             PG8_LDA(At, 0, 1); PG8_STAGE(PG8_SA(0, 0), a2, voffA);
;             PG8_BAR; PG8_WAIT_L(0); PG8_MMA(1, 0, At, B0); PG8_BAR; PG8_SCHED;
;             PG8_STAGE(PG8_SB(0, 1), b2 + hstep, voffB);
;             PG8_WAIT_V(6); PG8_BAR; PG8_MMA(1, 1, At, B1); PG8_BAR;
;             PG8_LDB(B0, 1, 0); PG8_SCHED; PG8_LDA(At, 1, 0); PG8_STAGE(PG8_SA(0, 1), a2 + hstep, voffA);
;             PG8_WAIT_L(8); PG8_BAR; PG8_WAIT_L(0); PG8_MMA(0, 0, At, B0); PG8_BAR; PG8_SCHED;
;             PG8_LDB(B1, 1, 1); PG8_STAGE(PG8_SB(1, 0), b3, voffB);
;             PG8_BAR; PG8_WAIT_L(0); PG8_MMA(0, 1, At, B1); PG8_BAR;
;             PG8_LDA(At, 1, 1); PG8_STAGE(PG8_SA(1, 0), a3, voffA);
;             PG8_BAR; PG8_WAIT_L(0); PG8_MMA(1, 0, At, B0); PG8_BAR; PG8_SCHED;
;             PG8_STAGE(PG8_SB(1, 1), b3 + hstep, voffB);
;             PG8_WAIT_V(6); PG8_BAR; PG8_MMA(1, 1, At, B1); PG8_BAR;
	ds_read_b128 v[128:131], v206 offset:32768
	ds_read_b128 v[132:135], v206 offset:33792
	ds_read_b128 v[136:139], v206 offset:34816
	ds_read_b128 v[140:143], v206 offset:35840
	s_mov_b32 m0, s74
	ds_read_b128 v[176:179], v206 offset:49152
	ds_read_b128 v[180:183], v206 offset:50176
	ds_read_b128 v[184:187], v206 offset:51200
	ds_read_b128 v[188:191], v206 offset:52224
	global_load_lds_dwordx4 v196, s[52:53]
	s_add_i32 m0, s74, 0x2000
	ds_read_b128 v[144:147], v247 offset:32768
	ds_read_b128 v[148:151], v247 offset:33792
	ds_read_b128 v[152:155], v247 offset:34816
	ds_read_b128 v[156:159], v247 offset:35840
	global_load_lds_dwordx4 v198, s[52:53]
	s_add_i32 m0, s74, 0x4000
	ds_read_b128 v[160:163], v247 offset:36864
	ds_read_b128 v[164:167], v247 offset:37888
	ds_read_b128 v[168:171], v247 offset:38912
	ds_read_b128 v[172:175], v247 offset:39936
	global_load_lds_dwordx4 v196, s[98:99]
	s_add_i32 m0, s74, 0x6000
	s_nop 0
	global_load_lds_dwordx4 v198, s[98:99]
	s_waitcnt lgkmcnt(0)
	s_barrier
	v_mfma_f32_16x16x32_bf16 v[124:127], v[128:131], v[144:147], v[124:127]
	v_mfma_f32_16x16x32_bf16 v[120:123], v[136:139], v[144:147], v[120:123]
	v_mfma_f32_16x16x32_bf16 v[116:119], v[128:131], v[152:155], v[116:119]
	v_mfma_f32_16x16x32_bf16 v[112:115], v[136:139], v[152:155], v[112:115]
	v_mfma_f32_16x16x32_bf16 v[108:111], v[128:131], v[160:163], v[108:111]
	v_mfma_f32_16x16x32_bf16 v[104:107], v[136:139], v[160:163], v[104:107]
	v_mfma_f32_16x16x32_bf16 v[100:103], v[128:131], v[168:171], v[100:103]
	v_mfma_f32_16x16x32_bf16 v[96:99], v[136:139], v[168:171], v[96:99]
	v_mfma_f32_16x16x32_bf16 v[124:127], v[132:135], v[148:151], v[124:127]
	v_mfma_f32_16x16x32_bf16 v[120:123], v[140:143], v[148:151], v[120:123]
	v_mfma_f32_16x16x32_bf16 v[116:119], v[132:135], v[156:159], v[116:119]
	v_mfma_f32_16x16x32_bf16 v[112:115], v[140:143], v[156:159], v[112:115]
	v_mfma_f32_16x16x32_bf16 v[108:111], v[132:135], v[164:167], v[108:111]
	v_mfma_f32_16x16x32_bf16 v[104:107], v[140:143], v[164:167], v[104:107]
	v_mfma_f32_16x16x32_bf16 v[100:103], v[132:135], v[172:175], v[100:103]
	v_mfma_f32_16x16x32_bf16 v[96:99], v[140:143], v[172:175], v[96:99]
	v_mfma_f32_16x16x32_bf16 v[92:95], v[176:179], v[144:147], v[92:95]
	v_mfma_f32_16x16x32_bf16 v[88:91], v[184:187], v[144:147], v[88:91]
	v_mfma_f32_16x16x32_bf16 v[84:87], v[176:179], v[152:155], v[84:87]
	v_mfma_f32_16x16x32_bf16 v[80:83], v[184:187], v[152:155], v[80:83]
	v_mfma_f32_16x16x32_bf16 v[76:79], v[176:179], v[160:163], v[76:79]
	v_mfma_f32_16x16x32_bf16 v[72:75], v[184:187], v[160:163], v[72:75]
	v_mfma_f32_16x16x32_bf16 v[68:71], v[176:179], v[168:171], v[68:71]
	v_mfma_f32_16x16x32_bf16 v[64:67], v[184:187], v[168:171], v[64:67]
	v_mfma_f32_16x16x32_bf16 v[92:95], v[180:183], v[148:151], v[92:95]
	v_mfma_f32_16x16x32_bf16 v[88:91], v[188:191], v[148:151], v[88:91]
	v_mfma_f32_16x16x32_bf16 v[84:87], v[180:183], v[156:159], v[84:87]
	v_mfma_f32_16x16x32_bf16 v[80:83], v[188:191], v[156:159], v[80:83]
	v_mfma_f32_16x16x32_bf16 v[76:79], v[180:183], v[164:167], v[76:79]
	v_mfma_f32_16x16x32_bf16 v[72:75], v[188:191], v[164:167], v[72:75]
	v_mfma_f32_16x16x32_bf16 v[68:71], v[180:183], v[172:175], v[68:71]
	v_mfma_f32_16x16x32_bf16 v[64:67], v[188:191], v[172:175], v[64:67]
	s_add_u32 s84, s46, 0x80
	s_addc_u32 s85, s47, 0
	s_add_u32 s98, s46, 0x40080
	s_addc_u32 s99, s47, 0
	s_add_i32 s55, s55, 2
	s_add_u32 s44, s44, 0x100
	s_addc_u32 s45, s45, 0
	s_add_u32 s41, s41, 0x100
	s_addc_u32 s43, s43, 0
	s_add_u32 s46, s44, 0xfffc0080
	s_addc_u32 s47, s45, -1
	s_cmp_eq_u32 s55, 12
	s_cselect_b32 s53, s7, s47
	s_cselect_b32 s52, s6, s46
	s_cselect_b32 s47, s9, s43
	s_cselect_b32 s46, s8, s41
	s_add_u32 s100, s44, 0xfffc0000
	s_addc_u32 s101, s45, -1
	s_barrier
; #define PG8_STAGE(bufoff, gbase, voff) do { _Pragma("unroll") for (int _i = 0; _i < 2; ++_i) \
;         __builtin_amdgcn_global_load_lds((const unsigned*)((const char*)(gbase) + (voff)[_i]), (LAS unsigned*)(lds + (bufoff) + ldsw + _i * 8192), 16, 0, 0); } while (0)
; #define PG8_WAIT_V(n) asm volatile("s_waitcnt vmcnt(" #n ")" ::: "memory")
; #define PG8_WAIT_L(n) asm volatile("s_waitcnt lgkmcnt(" #n ")" ::: "memory")
; template <class Prog>
; __device__ __forceinline__ void gemm_phase(LAS unsigned char* lds, const int K, const Prog& S) {
;     ...
;         for (int t = 0; t < nt; t += 2) {
;             const bool last = (t == nt - 2);
;             const char* a1 = cA + (size_t)(t + 1) * kstep;
;             const char* a2 = last ? nA : cA + (size_t)(t + 2) * kstep; const char* b2 = last ? nB : cB + (size_t)(t + 2) * kstep;
;             const char* a3 = a2 + kstep; const char* b3 = b2 + kstep;
;             PG8_LDB(B0, 0, 0); PG8_SCHED; PG8_LDA(At, 0, 0); PG8_STAGE(PG8_SA(1, 1), a1 + hstep, voffA);
;             PG8_WAIT_L(8); PG8_BAR; PG8_WAIT_L(0); PG8_MMA(0, 0, At, B0); PG8_BAR; PG8_SCHED;
;             PG8_LDB(B1, 0, 1); PG8_STAGE(PG8_SB(0, 0), b2, voffB);
;             PG8_BAR; PG8_WAIT_L(0); PG8_MMA(0, 1, At, B1); PG8_BAR;
;             PG8_LDA(At, 0, 1); PG8_STAGE(PG8_SA(0, 0), a2, voffA);
;             PG8_BAR; PG8_WAIT_L(0); PG8_MMA(1, 0, At, B0); PG8_BAR; PG8_SCHED;
;             PG8_STAGE(PG8_SB(0, 1), b2 + hstep, voffB);
;             PG8_WAIT_V(6); PG8_BAR; PG8_MMA(1, 1, At, B1); PG8_BAR;
;             PG8_LDB(B0, 1, 0); PG8_SCHED; PG8_LDA(At, 1, 0); PG8_STAGE(PG8_SA(0, 1), a2 + hstep, voffA);
;             PG8_WAIT_L(8); PG8_BAR; PG8_WAIT_L(0); PG8_MMA(0, 0, At, B0); PG8_BAR; PG8_SCHED;
;             PG8_LDB(B1, 1, 1); PG8_STAGE(PG8_SB(1, 0), b3, voffB);
;             PG8_BAR; PG8_WAIT_L(0); PG8_MMA(0, 1, At, B1); PG8_BAR;
;             PG8_LDA(At, 1, 1); PG8_STAGE(PG8_SA(1, 0), a3, voffA);
;             PG8_BAR; PG8_WAIT_L(0); PG8_MMA(1, 0, At, B0); PG8_BAR; PG8_SCHED;
;             PG8_STAGE(PG8_SB(1, 1), b3 + hstep, voffB);
;             PG8_WAIT_V(6); PG8_BAR; PG8_MMA(1, 1, At, B1); PG8_BAR;
;     __device__ __forceinline__ void epi(f32x4 (&acc)[2][2][4][2], const pg8::Unit& u, int wr, int wc, int fr, int fq) const {
;     ...
;         const int sub = u.sub;
;         u32x4 gn[4][2][2], gd[4][2][2];
;         const int dsub = sub < 2 ? sub + 1 : sub;
	ds_read_b128 v[144:147], v247 offset:49152
	ds_read_b128 v[148:151], v247 offset:50176
	ds_read_b128 v[152:155], v247 offset:51200
	ds_read_b128 v[156:159], v247 offset:52224
	s_add_i32 m0, s74, 0x18000
	ds_read_b128 v[160:163], v247 offset:53248
	ds_read_b128 v[164:167], v247 offset:54272
	ds_read_b128 v[168:171], v247 offset:55296
	ds_read_b128 v[172:175], v247 offset:56320
	global_load_lds_dwordx4 v192, s[84:85]
	s_add_i32 m0, s74, 0x1a000
	s_nop 0
	global_load_lds_dwordx4 v200, s[84:85]
	s_add_i32 m0, s74, 0x1c000
	s_nop 0
	global_load_lds_dwordx4 v192, s[98:99]
	s_add_i32 m0, s74, 0x1e000
	s_nop 0
	global_load_lds_dwordx4 v200, s[98:99]
	s_waitcnt vmcnt(4)
	s_waitcnt lgkmcnt(0)
	s_barrier
	v_mfma_f32_16x16x32_bf16 v[60:63], v[128:131], v[144:147], v[60:63]
	v_mfma_f32_16x16x32_bf16 v[56:59], v[136:139], v[144:147], v[56:59]
	v_mfma_f32_16x16x32_bf16 v[52:55], v[128:131], v[152:155], v[52:55]
	v_mfma_f32_16x16x32_bf16 v[48:51], v[136:139], v[152:155], v[48:51]
	v_mfma_f32_16x16x32_bf16 v[44:47], v[128:131], v[160:163], v[44:47]
	v_mfma_f32_16x16x32_bf16 v[40:43], v[136:139], v[160:163], v[40:43]
	v_mfma_f32_16x16x32_bf16 v[36:39], v[128:131], v[168:171], v[36:39]
	v_mfma_f32_16x16x32_bf16 v[32:35], v[136:139], v[168:171], v[32:35]
	v_mfma_f32_16x16x32_bf16 v[60:63], v[132:135], v[148:151], v[60:63]
	v_mfma_f32_16x16x32_bf16 v[56:59], v[140:143], v[148:151], v[56:59]
	v_mfma_f32_16x16x32_bf16 v[52:55], v[132:135], v[156:159], v[52:55]
	v_mfma_f32_16x16x32_bf16 v[48:51], v[140:143], v[156:159], v[48:51]
	v_mfma_f32_16x16x32_bf16 v[44:47], v[132:135], v[164:167], v[44:47]
	v_mfma_f32_16x16x32_bf16 v[40:43], v[140:143], v[164:167], v[40:43]
	v_mfma_f32_16x16x32_bf16 v[36:39], v[132:135], v[172:175], v[36:39]
	v_mfma_f32_16x16x32_bf16 v[32:35], v[140:143], v[172:175], v[32:35]
	v_mfma_f32_16x16x32_bf16 v[28:31], v[176:179], v[144:147], v[28:31]
	v_mfma_f32_16x16x32_bf16 v[24:27], v[184:187], v[144:147], v[24:27]
	v_mfma_f32_16x16x32_bf16 v[20:23], v[176:179], v[152:155], v[20:23]
	v_mfma_f32_16x16x32_bf16 v[16:19], v[184:187], v[152:155], v[16:19]
	v_mfma_f32_16x16x32_bf16 v[12:15], v[176:179], v[160:163], v[12:15]
	v_mfma_f32_16x16x32_bf16 v[8:11], v[184:187], v[160:163], v[8:11]
	v_mfma_f32_16x16x32_bf16 v[4:7], v[176:179], v[168:171], v[4:7]
	v_mfma_f32_16x16x32_bf16 v[0:3], v[184:187], v[168:171], v[0:3]
	v_mfma_f32_16x16x32_bf16 v[28:31], v[180:183], v[148:151], v[28:31]
	v_mfma_f32_16x16x32_bf16 v[24:27], v[188:191], v[148:151], v[24:27]
	v_mfma_f32_16x16x32_bf16 v[20:23], v[180:183], v[156:159], v[20:23]
	v_mfma_f32_16x16x32_bf16 v[16:19], v[188:191], v[156:159], v[16:19]
	v_mfma_f32_16x16x32_bf16 v[12:15], v[180:183], v[164:167], v[12:15]
	v_mfma_f32_16x16x32_bf16 v[8:11], v[188:191], v[164:167], v[8:11]
	v_mfma_f32_16x16x32_bf16 v[4:7], v[180:183], v[172:175], v[4:7]
	v_mfma_f32_16x16x32_bf16 v[0:3], v[188:191], v[172:175], v[0:3]
	s_cmp_gt_u32 s55, 13
	s_barrier
	s_cbranch_scc0 .LBB0_400
	s_cmp_lt_i32 s14, 2
	v_lshl_add_u32 v208, s15, 8, v244
	v_lshl_or_b32 v206, s54, 8, v246
	s_cselect_b64 s[8:9], -1, 0
	s_cmp_gt_i32 s14, 1
	v_mov_b64_e32 v[128:129], s[26:27]
	s_cselect_b64 s[92:93], -1, 0
	s_cmp_lg_u64 s[8:9], 0
	v_ashrrev_i32_e32 v207, 31, v206
	v_mad_i64_i32 v[128:129], s[6:7], v208, s58, v[128:129]
	s_addc_u32 s15, s14, 0
	s_lshl_b32 s46, s14, 11
	v_lshl_add_u64 v[128:129], v[206:207], 1, v[128:129]
	s_ashr_i32 s47, s46, 31
	v_lshl_add_u64 v[128:129], v[128:129], 0, s[34:35]
	v_lshl_add_u64 v[130:131], s[46:47], 1, v[128:129]
	global_load_dwordx4 v[188:191], v[130:131], off
	s_lshl_b32 s52, s15, 11
	s_ashr_i32 s53, s52, 31
	v_mov_b32_e32 v148, 0
	s_and_b64 vcc, exec, s[92:93]
	v_lshl_add_u64 v[128:129], s[52:53], 1, v[128:129]
	v_mov_b32_e32 v180, 0
	v_mov_b32_e32 v181, 0
	v_mov_b32_e32 v182, 0
	v_mov_b32_e32 v183, 0
	s_cbranch_vccnz .LBB0_403
	global_load_dwordx4 v[180:183], v[128:129], off

; #define PG8_STAGE(bufoff, gbase, voff) do { _Pragma("unroll") for (int _i = 0; _i < 2; ++_i) \
;         __builtin_amdgcn_global_load_lds((const unsigned*)((const char*)(gbase) + (voff)[_i]), (LAS unsigned*)(lds + (bufoff) + ldsw + _i * 8192), 16, 0, 0); } while (0)
; #define PG8_LDA(dst, b, h) do { _Pragma("unroll") for (int m = 0; m < 4; ++m) _Pragma("unroll") for (int k = 0; k < 2; ++k) dst[m][k] = *(const LAS bf16x8*)(lds + PG8_SA(b, h) + aoff + m * 2048 + k * 1024); } while (0)
; #define PG8_WAIT_V(n) asm volatile("s_waitcnt vmcnt(" #n ")" ::: "memory")
; template <class Prog>
; __device__ __forceinline__ void gemm_phase(LAS unsigned char* lds, const int K, const Prog& S) {
;     ...
;         const char* nA = has_next ? nxt.a : cA; const char* nB = has_next ? nxt.b : cB;
;         for (int t = 0; t < nt; t += 2) {
;             const bool last = (t == nt - 2);
;             const char* a1 = cA + (size_t)(t + 1) * kstep;
;             const char* a2 = last ? nA : cA + (size_t)(t + 2) * kstep; const char* b2 = last ? nB : cB + (size_t)(t + 2) * kstep;
;             const char* a3 = a2 + kstep; const char* b3 = b2 + kstep;
;             PG8_LDB(B0, 0, 0); PG8_SCHED; PG8_LDA(At, 0, 0); PG8_STAGE(PG8_SA(1, 1), a1 + hstep, voffA);
;             PG8_WAIT_L(8); PG8_BAR; PG8_WAIT_L(0); PG8_MMA(0, 0, At, B0); PG8_BAR; PG8_SCHED;
;             PG8_LDB(B1, 0, 1); PG8_STAGE(PG8_SB(0, 0), b2, voffB);
;             PG8_BAR; PG8_WAIT_L(0); PG8_MMA(0, 1, At, B1); PG8_BAR;
;             PG8_LDA(At, 0, 1); PG8_STAGE(PG8_SA(0, 0), a2, voffA);
;             PG8_BAR; PG8_WAIT_L(0); PG8_MMA(1, 0, At, B0); PG8_BAR; PG8_SCHED;
;             PG8_STAGE(PG8_SB(0, 1), b2 + hstep, voffB);
;             PG8_WAIT_V(6); PG8_BAR; PG8_MMA(1, 1, At, B1); PG8_BAR;
;             PG8_LDB(B0, 1, 0); PG8_SCHED; PG8_LDA(At, 1, 0); PG8_STAGE(PG8_SA(0, 1), a2 + hstep, voffA);
;             PG8_WAIT_L(8); PG8_BAR; PG8_WAIT_L(0); PG8_MMA(0, 0, At, B0); PG8_BAR; PG8_SCHED;
;             PG8_LDB(B1, 1, 1); PG8_STAGE(PG8_SB(1, 0), b3, voffB);
;             PG8_BAR; PG8_WAIT_L(0); PG8_MMA(0, 1, At, B1); PG8_BAR;
;             PG8_LDA(At, 1, 1); PG8_STAGE(PG8_SA(1, 0), a3, voffA);
;             PG8_BAR; PG8_WAIT_L(0); PG8_MMA(1, 0, At, B0); PG8_BAR; PG8_SCHED;
;             PG8_STAGE(PG8_SB(1, 1), b3 + hstep, voffB);
;             PG8_WAIT_V(6); PG8_BAR; PG8_MMA(1, 1, At, B1); PG8_BAR;
.LBB0_570:
	s_add_u32 s46, s46, 0x80080
	s_addc_u32 s47, s47, 0
	s_add_u32 s41, s52, 0x100
	s_addc_u32 s43, s53, 0
	s_mov_b32 s54, -2
	s_waitcnt lgkmcnt(0)
	s_waitcnt vmcnt(16)
	v_add_u32_e32 v202, 0x10000, v215
	s_add_u32 s52, s46, 0xfff80080
	s_addc_u32 s53, s47, -1
	s_cmp_eq_u32 s54, 28
	s_cselect_b32 s93, s7, s53
	s_cselect_b32 s92, s6, s52
	s_cselect_b32 s53, s45, s43
	s_cselect_b32 s52, s44, s41
	s_add_u32 s100, s46, 0xfff80000
	s_addc_u32 s101, s47, -1
	ds_read_b128 v[128:131], v202
	ds_read_b128 v[132:135], v202 offset:1024
	ds_read_b128 v[136:139], v202 offset:2048
	ds_read_b128 v[140:143], v202 offset:3072
	s_add_i32 m0, s75, 0x8000
	ds_read_b128 v[176:179], v202 offset:16384
	ds_read_b128 v[180:183], v202 offset:17408
	ds_read_b128 v[184:187], v202 offset:18432
	ds_read_b128 v[198:201], v202 offset:19456
	global_load_lds_dwordx4 v190, s[100:101]
	s_add_i32 m0, s75, 0xa000
	ds_read_b128 v[144:147], v217
	ds_read_b128 v[148:151], v217 offset:1024
	ds_read_b128 v[152:155], v217 offset:2048
	ds_read_b128 v[156:159], v217 offset:3072
	global_load_lds_dwordx4 v196, s[100:101]
	s_add_i32 m0, s75, 0xc000
	ds_read_b128 v[160:163], v217 offset:4096
	ds_read_b128 v[164:167], v217 offset:5120
	ds_read_b128 v[168:171], v217 offset:6144
	ds_read_b128 v[172:175], v217 offset:7168
	global_load_lds_dwordx4 v190, s[46:47]
	s_add_i32 m0, s75, 0xe000
	s_nop 0
	global_load_lds_dwordx4 v196, s[46:47]
	s_waitcnt lgkmcnt(0)
	s_barrier
	v_mfma_f32_16x16x32_bf16 v[124:127], v[128:131], v[144:147], 0
	v_mfma_f32_16x16x32_bf16 v[120:123], v[136:139], v[144:147], 0
	v_mfma_f32_16x16x32_bf16 v[108:111], v[128:131], v[152:155], 0
	v_mfma_f32_16x16x32_bf16 v[104:107], v[136:139], v[152:155], 0
	v_mfma_f32_16x16x32_bf16 v[92:95], v[128:131], v[160:163], 0
	v_mfma_f32_16x16x32_bf16 v[88:91], v[136:139], v[160:163], 0
	v_mfma_f32_16x16x32_bf16 v[76:79], v[128:131], v[168:171], 0
	v_mfma_f32_16x16x32_bf16 v[72:75], v[136:139], v[168:171], 0
	v_mfma_f32_16x16x32_bf16 v[124:127], v[132:135], v[148:151], v[124:127]
	v_mfma_f32_16x16x32_bf16 v[120:123], v[140:143], v[148:151], v[120:123]
	v_mfma_f32_16x16x32_bf16 v[108:111], v[132:135], v[156:159], v[108:111]
	v_mfma_f32_16x16x32_bf16 v[104:107], v[140:143], v[156:159], v[104:107]
	v_mfma_f32_16x16x32_bf16 v[92:95], v[132:135], v[164:167], v[92:95]
	v_mfma_f32_16x16x32_bf16 v[88:91], v[140:143], v[164:167], v[88:91]
	v_mfma_f32_16x16x32_bf16 v[76:79], v[132:135], v[172:175], v[76:79]
	v_mfma_f32_16x16x32_bf16 v[72:75], v[140:143], v[172:175], v[72:75]
	v_mfma_f32_16x16x32_bf16 v[116:119], v[176:179], v[144:147], 0
	v_mfma_f32_16x16x32_bf16 v[112:115], v[184:187], v[144:147], 0
	v_mfma_f32_16x16x32_bf16 v[100:103], v[176:179], v[152:155], 0
	v_mfma_f32_16x16x32_bf16 v[96:99], v[184:187], v[152:155], 0
	v_mfma_f32_16x16x32_bf16 v[84:87], v[176:179], v[160:163], 0
	v_mfma_f32_16x16x32_bf16 v[80:83], v[184:187], v[160:163], 0
	v_mfma_f32_16x16x32_bf16 v[68:71], v[176:179], v[168:171], 0
	v_mfma_f32_16x16x32_bf16 v[64:67], v[184:187], v[168:171], 0
	v_mfma_f32_16x16x32_bf16 v[116:119], v[180:183], v[148:151], v[116:119]
	v_mfma_f32_16x16x32_bf16 v[112:115], v[198:201], v[148:151], v[112:115]
	v_mfma_f32_16x16x32_bf16 v[100:103], v[180:183], v[156:159], v[100:103]
	v_mfma_f32_16x16x32_bf16 v[96:99], v[198:201], v[156:159], v[96:99]
	v_mfma_f32_16x16x32_bf16 v[84:87], v[180:183], v[164:167], v[84:87]
	v_mfma_f32_16x16x32_bf16 v[80:83], v[198:201], v[164:167], v[80:83]
	v_mfma_f32_16x16x32_bf16 v[68:71], v[180:183], v[172:175], v[68:71]
	v_mfma_f32_16x16x32_bf16 v[64:67], v[198:201], v[172:175], v[64:67]
	s_add_u32 vcc_lo, s52, 0x80000
	s_addc_u32 vcc_hi, s53, 0
	s_add_u32 s98, s92, 0x80000
	s_addc_u32 s99, s93, 0
	s_barrier
	ds_read_b128 v[144:147], v217 offset:16384
	ds_read_b128 v[148:151], v217 offset:17408
	ds_read_b128 v[152:155], v217 offset:18432
	ds_read_b128 v[156:159], v217 offset:19456
	s_add_i32 m0, s75, 0x10000
	ds_read_b128 v[160:163], v217 offset:20480
	ds_read_b128 v[164:167], v217 offset:21504
	ds_read_b128 v[168:171], v217 offset:22528
	ds_read_b128 v[172:175], v217 offset:23552
	global_load_lds_dwordx4 v192, s[52:53]
	s_add_i32 m0, s75, 0x12000
	s_nop 0
	global_load_lds_dwordx4 v188, s[52:53]
	s_add_i32 m0, s75, 0x14000
	s_nop 0
	global_load_lds_dwordx4 v192, vcc
	s_add_i32 m0, s75, 0x16000
	s_nop 0
	global_load_lds_dwordx4 v188, vcc
	s_waitcnt vmcnt(4)
	s_waitcnt lgkmcnt(0)
	s_barrier
	v_mfma_f32_16x16x32_bf16 v[60:63], v[128:131], v[144:147], 0
	v_mfma_f32_16x16x32_bf16 v[56:59], v[136:139], v[144:147], 0
	v_mfma_f32_16x16x32_bf16 v[44:47], v[128:131], v[152:155], 0
	v_mfma_f32_16x16x32_bf16 v[40:43], v[136:139], v[152:155], 0
	v_mfma_f32_16x16x32_bf16 v[28:31], v[128:131], v[160:163], 0
	v_mfma_f32_16x16x32_bf16 v[24:27], v[136:139], v[160:163], 0
	v_mfma_f32_16x16x32_bf16 v[12:15], v[128:131], v[168:171], 0
	v_mfma_f32_16x16x32_bf16 v[8:11], v[136:139], v[168:171], 0
	v_mfma_f32_16x16x32_bf16 v[60:63], v[132:135], v[148:151], v[60:63]
	v_mfma_f32_16x16x32_bf16 v[56:59], v[140:143], v[148:151], v[56:59]
	v_mfma_f32_16x16x32_bf16 v[44:47], v[132:135], v[156:159], v[44:47]
	v_mfma_f32_16x16x32_bf16 v[40:43], v[140:143], v[156:159], v[40:43]
	v_mfma_f32_16x16x32_bf16 v[28:31], v[132:135], v[164:167], v[28:31]
	v_mfma_f32_16x16x32_bf16 v[24:27], v[140:143], v[164:167], v[24:27]
	v_mfma_f32_16x16x32_bf16 v[12:15], v[132:135], v[172:175], v[12:15]
	v_mfma_f32_16x16x32_bf16 v[8:11], v[140:143], v[172:175], v[8:11]
	v_mfma_f32_16x16x32_bf16 v[52:55], v[176:179], v[144:147], 0
	v_mfma_f32_16x16x32_bf16 v[48:51], v[184:187], v[144:147], 0
	v_mfma_f32_16x16x32_bf16 v[36:39], v[176:179], v[152:155], 0
	v_mfma_f32_16x16x32_bf16 v[32:35], v[184:187], v[152:155], 0
	v_mfma_f32_16x16x32_bf16 v[20:23], v[176:179], v[160:163], 0
	v_mfma_f32_16x16x32_bf16 v[16:19], v[184:187], v[160:163], 0
	v_mfma_f32_16x16x32_bf16 v[4:7], v[176:179], v[168:171], 0
	v_mfma_f32_16x16x32_bf16 v[0:3], v[184:187], v[168:171], 0
	v_mfma_f32_16x16x32_bf16 v[52:55], v[180:183], v[148:151], v[52:55]
	v_mfma_f32_16x16x32_bf16 v[48:51], v[198:201], v[148:151], v[48:51]
	v_mfma_f32_16x16x32_bf16 v[36:39], v[180:183], v[156:159], v[36:39]
	v_mfma_f32_16x16x32_bf16 v[32:35], v[198:201], v[156:159], v[32:35]
	v_mfma_f32_16x16x32_bf16 v[20:23], v[180:183], v[164:167], v[20:23]
	v_mfma_f32_16x16x32_bf16 v[16:19], v[198:201], v[164:167], v[16:19]
	v_mfma_f32_16x16x32_bf16 v[4:7], v[180:183], v[172:175], v[4:7]
	v_mfma_f32_16x16x32_bf16 v[0:3], v[198:201], v[172:175], v[0:3]
	s_barrier
; #define PG8_STAGE(bufoff, gbase, voff) do { _Pragma("unroll") for (int _i = 0; _i < 2; ++_i) \
;         __builtin_amdgcn_global_load_lds((const unsigned*)((const char*)(gbase) + (voff)[_i]), (LAS unsigned*)(lds + (bufoff) + ldsw + _i * 8192), 16, 0, 0); } while (0)
; #define PG8_LDA(dst, b, h) do { _Pragma("unroll") for (int m = 0; m < 4; ++m) _Pragma("unroll") for (int k = 0; k < 2; ++k) dst[m][k] = *(const LAS bf16x8*)(lds + PG8_SA(b, h) + aoff + m * 2048 + k * 1024); } while (0)
; #define PG8_WAIT_V(n) asm volatile("s_waitcnt vmcnt(" #n ")" ::: "memory")
; #define PG8_WAIT_L(n) asm volatile("s_waitcnt lgkmcnt(" #n ")" ::: "memory")
; template <class Prog>
; __device__ __forceinline__ void gemm_phase(LAS unsigned char* lds, const int K, const Prog& S) {
;     ...
;         for (int t = 0; t < nt; t += 2) {
;             const bool last = (t == nt - 2);
;             const char* a1 = cA + (size_t)(t + 1) * kstep;
;             const char* a2 = last ? nA : cA + (size_t)(t + 2) * kstep; const char* b2 = last ? nB : cB + (size_t)(t + 2) * kstep;
;             const char* a3 = a2 + kstep; const char* b3 = b2 + kstep;
;             PG8_LDB(B0, 0, 0); PG8_SCHED; PG8_LDA(At, 0, 0); PG8_STAGE(PG8_SA(1, 1), a1 + hstep, voffA);
;             PG8_WAIT_L(8); PG8_BAR; PG8_WAIT_L(0); PG8_MMA(0, 0, At, B0); PG8_BAR; PG8_SCHED;
;             PG8_LDB(B1, 0, 1); PG8_STAGE(PG8_SB(0, 0), b2, voffB);
;             PG8_BAR; PG8_WAIT_L(0); PG8_MMA(0, 1, At, B1); PG8_BAR;
;             PG8_LDA(At, 0, 1); PG8_STAGE(PG8_SA(0, 0), a2, voffA);
;             PG8_BAR; PG8_WAIT_L(0); PG8_MMA(1, 0, At, B0); PG8_BAR; PG8_SCHED;
;             PG8_STAGE(PG8_SB(0, 1), b2 + hstep, voffB);
;             PG8_WAIT_V(6); PG8_BAR; PG8_MMA(1, 1, At, B1); PG8_BAR;
;             PG8_LDB(B0, 1, 0); PG8_SCHED; PG8_LDA(At, 1, 0); PG8_STAGE(PG8_SA(0, 1), a2 + hstep, voffA);
;             PG8_WAIT_L(8); PG8_BAR; PG8_WAIT_L(0); PG8_MMA(0, 0, At, B0); PG8_BAR; PG8_SCHED;
;             PG8_LDB(B1, 1, 1); PG8_STAGE(PG8_SB(1, 0), b3, voffB);
;             PG8_BAR; PG8_WAIT_L(0); PG8_MMA(0, 1, At, B1); PG8_BAR;
;             PG8_LDA(At, 1, 1); PG8_STAGE(PG8_SA(1, 0), a3, voffA);
;             PG8_BAR; PG8_WAIT_L(0); PG8_MMA(1, 0, At, B0); PG8_BAR; PG8_SCHED;
;             PG8_STAGE(PG8_SB(1, 1), b3 + hstep, voffB);
;             PG8_WAIT_V(6); PG8_BAR; PG8_MMA(1, 1, At, B1); PG8_BAR;
	ds_read_b128 v[128:131], v202 offset:32768
	ds_read_b128 v[132:135], v202 offset:33792
	ds_read_b128 v[136:139], v202 offset:34816
	ds_read_b128 v[140:143], v202 offset:35840
	s_mov_b32 m0, s75
	ds_read_b128 v[176:179], v202 offset:49152
	ds_read_b128 v[180:183], v202 offset:50176
	ds_read_b128 v[184:187], v202 offset:51200
	ds_read_b128 v[198:201], v202 offset:52224
	global_load_lds_dwordx4 v192, s[92:93]
	s_add_i32 m0, s75, 0x2000
	ds_read_b128 v[144:147], v217 offset:32768
	ds_read_b128 v[148:151], v217 offset:33792
	ds_read_b128 v[152:155], v217 offset:34816
	ds_read_b128 v[156:159], v217 offset:35840
	global_load_lds_dwordx4 v188, s[92:93]
	s_add_i32 m0, s75, 0x4000
	ds_read_b128 v[160:163], v217 offset:36864
	ds_read_b128 v[164:167], v217 offset:37888
	ds_read_b128 v[168:171], v217 offset:38912
	ds_read_b128 v[172:175], v217 offset:39936
	global_load_lds_dwordx4 v192, s[98:99]
	s_add_i32 m0, s75, 0x6000
	s_nop 0
	global_load_lds_dwordx4 v188, s[98:99]
	s_waitcnt lgkmcnt(0)
	s_barrier
	v_mfma_f32_16x16x32_bf16 v[124:127], v[128:131], v[144:147], v[124:127]
	v_mfma_f32_16x16x32_bf16 v[120:123], v[136:139], v[144:147], v[120:123]
	v_mfma_f32_16x16x32_bf16 v[108:111], v[128:131], v[152:155], v[108:111]
	v_mfma_f32_16x16x32_bf16 v[104:107], v[136:139], v[152:155], v[104:107]
	v_mfma_f32_16x16x32_bf16 v[92:95], v[128:131], v[160:163], v[92:95]
	v_mfma_f32_16x16x32_bf16 v[88:91], v[136:139], v[160:163], v[88:91]
	v_mfma_f32_16x16x32_bf16 v[76:79], v[128:131], v[168:171], v[76:79]
	v_mfma_f32_16x16x32_bf16 v[72:75], v[136:139], v[168:171], v[72:75]
	v_mfma_f32_16x16x32_bf16 v[124:127], v[132:135], v[148:151], v[124:127]
	v_mfma_f32_16x16x32_bf16 v[120:123], v[140:143], v[148:151], v[120:123]
	v_mfma_f32_16x16x32_bf16 v[108:111], v[132:135], v[156:159], v[108:111]
	v_mfma_f32_16x16x32_bf16 v[104:107], v[140:143], v[156:159], v[104:107]
	v_mfma_f32_16x16x32_bf16 v[92:95], v[132:135], v[164:167], v[92:95]
	v_mfma_f32_16x16x32_bf16 v[88:91], v[140:143], v[164:167], v[88:91]
	v_mfma_f32_16x16x32_bf16 v[76:79], v[132:135], v[172:175], v[76:79]
	v_mfma_f32_16x16x32_bf16 v[72:75], v[140:143], v[172:175], v[72:75]
	v_mfma_f32_16x16x32_bf16 v[116:119], v[176:179], v[144:147], v[116:119]
	v_mfma_f32_16x16x32_bf16 v[112:115], v[184:187], v[144:147], v[112:115]
	v_mfma_f32_16x16x32_bf16 v[100:103], v[176:179], v[152:155], v[100:103]
	v_mfma_f32_16x16x32_bf16 v[96:99], v[184:187], v[152:155], v[96:99]
	v_mfma_f32_16x16x32_bf16 v[84:87], v[176:179], v[160:163], v[84:87]
	v_mfma_f32_16x16x32_bf16 v[80:83], v[184:187], v[160:163], v[80:83]
	v_mfma_f32_16x16x32_bf16 v[68:71], v[176:179], v[168:171], v[68:71]
	v_mfma_f32_16x16x32_bf16 v[64:67], v[184:187], v[168:171], v[64:67]
	v_mfma_f32_16x16x32_bf16 v[116:119], v[180:183], v[148:151], v[116:119]
	v_mfma_f32_16x16x32_bf16 v[112:115], v[198:201], v[148:151], v[112:115]
	v_mfma_f32_16x16x32_bf16 v[100:103], v[180:183], v[156:159], v[100:103]
	v_mfma_f32_16x16x32_bf16 v[96:99], v[198:201], v[156:159], v[96:99]
	v_mfma_f32_16x16x32_bf16 v[84:87], v[180:183], v[164:167], v[84:87]
	v_mfma_f32_16x16x32_bf16 v[80:83], v[198:201], v[164:167], v[80:83]
	v_mfma_f32_16x16x32_bf16 v[68:71], v[180:183], v[172:175], v[68:71]
	v_mfma_f32_16x16x32_bf16 v[64:67], v[198:201], v[172:175], v[64:67]
	s_add_u32 vcc_lo, s52, 0x80
	s_addc_u32 vcc_hi, s53, 0
	s_add_u32 s98, s52, 0x80080
	s_addc_u32 s99, s53, 0
	s_add_i32 s54, s54, 2
	s_add_u32 s46, s46, 0x100
	s_addc_u32 s47, s47, 0
	s_add_u32 s41, s41, 0x100
	s_addc_u32 s43, s43, 0
	s_add_u32 s52, s46, 0xfff80080
	s_addc_u32 s53, s47, -1
	s_cmp_eq_u32 s54, 28
	s_cselect_b32 s93, s7, s53
	s_cselect_b32 s92, s6, s52
	s_cselect_b32 s53, s45, s43
	s_cselect_b32 s52, s44, s41
	s_add_u32 s100, s46, 0xfff80000
	s_addc_u32 s101, s47, -1
	s_barrier
	ds_read_b128 v[144:147], v217 offset:49152
	ds_read_b128 v[148:151], v217 offset:50176
	ds_read_b128 v[152:155], v217 offset:51200
	ds_read_b128 v[156:159], v217 offset:52224
	s_add_i32 m0, s75, 0x18000
	ds_read_b128 v[160:163], v217 offset:53248
	ds_read_b128 v[164:167], v217 offset:54272
	ds_read_b128 v[168:171], v217 offset:55296
	ds_read_b128 v[172:175], v217 offset:56320
	global_load_lds_dwordx4 v192, vcc
	s_add_i32 m0, s75, 0x1a000
	s_nop 0
	global_load_lds_dwordx4 v188, vcc
	s_add_i32 m0, s75, 0x1c000
	s_nop 0
	global_load_lds_dwordx4 v192, s[98:99]
	s_add_i32 m0, s75, 0x1e000
	s_nop 0
	global_load_lds_dwordx4 v188, s[98:99]
	s_waitcnt vmcnt(4)
	s_waitcnt lgkmcnt(0)
	s_barrier
	v_mfma_f32_16x16x32_bf16 v[60:63], v[128:131], v[144:147], v[60:63]
	v_mfma_f32_16x16x32_bf16 v[56:59], v[136:139], v[144:147], v[56:59]
	v_mfma_f32_16x16x32_bf16 v[44:47], v[128:131], v[152:155], v[44:47]
	v_mfma_f32_16x16x32_bf16 v[40:43], v[136:139], v[152:155], v[40:43]
	v_mfma_f32_16x16x32_bf16 v[28:31], v[128:131], v[160:163], v[28:31]
	v_mfma_f32_16x16x32_bf16 v[24:27], v[136:139], v[160:163], v[24:27]
	v_mfma_f32_16x16x32_bf16 v[12:15], v[128:131], v[168:171], v[12:15]
	v_mfma_f32_16x16x32_bf16 v[8:11], v[136:139], v[168:171], v[8:11]
	v_mfma_f32_16x16x32_bf16 v[60:63], v[132:135], v[148:151], v[60:63]
	v_mfma_f32_16x16x32_bf16 v[56:59], v[140:143], v[148:151], v[56:59]
	v_mfma_f32_16x16x32_bf16 v[44:47], v[132:135], v[156:159], v[44:47]
	v_mfma_f32_16x16x32_bf16 v[40:43], v[140:143], v[156:159], v[40:43]
	v_mfma_f32_16x16x32_bf16 v[28:31], v[132:135], v[164:167], v[28:31]
	v_mfma_f32_16x16x32_bf16 v[24:27], v[140:143], v[164:167], v[24:27]
	v_mfma_f32_16x16x32_bf16 v[12:15], v[132:135], v[172:175], v[12:15]
	v_mfma_f32_16x16x32_bf16 v[8:11], v[140:143], v[172:175], v[8:11]
	v_mfma_f32_16x16x32_bf16 v[52:55], v[176:179], v[144:147], v[52:55]
	v_mfma_f32_16x16x32_bf16 v[48:51], v[184:187], v[144:147], v[48:51]
	v_mfma_f32_16x16x32_bf16 v[36:39], v[176:179], v[152:155], v[36:39]
	v_mfma_f32_16x16x32_bf16 v[32:35], v[184:187], v[152:155], v[32:35]
	v_mfma_f32_16x16x32_bf16 v[20:23], v[176:179], v[160:163], v[20:23]
	v_mfma_f32_16x16x32_bf16 v[16:19], v[184:187], v[160:163], v[16:19]
	v_mfma_f32_16x16x32_bf16 v[4:7], v[176:179], v[168:171], v[4:7]
	v_mfma_f32_16x16x32_bf16 v[0:3], v[184:187], v[168:171], v[0:3]
	v_mfma_f32_16x16x32_bf16 v[52:55], v[180:183], v[148:151], v[52:55]
	v_mfma_f32_16x16x32_bf16 v[48:51], v[198:201], v[148:151], v[48:51]
	v_mfma_f32_16x16x32_bf16 v[36:39], v[180:183], v[156:159], v[36:39]
	v_mfma_f32_16x16x32_bf16 v[32:35], v[198:201], v[156:159], v[32:35]
	v_mfma_f32_16x16x32_bf16 v[20:23], v[180:183], v[164:167], v[20:23]
	v_mfma_f32_16x16x32_bf16 v[16:19], v[198:201], v[164:167], v[16:19]
	v_mfma_f32_16x16x32_bf16 v[4:7], v[180:183], v[172:175], v[4:7]
	v_mfma_f32_16x16x32_bf16 v[0:3], v[198:201], v[172:175], v[0:3]
	s_cmp_gt_u32 s54, 29
	s_barrier
	.p2align 6
; #define PG8_STAGE(bufoff, gbase, voff) do { _Pragma("unroll") for (int _i = 0; _i < 2; ++_i) \
;         __builtin_amdgcn_global_load_lds((const unsigned*)((const char*)(gbase) + (voff)[_i]), (LAS unsigned*)(lds + (bufoff) + ldsw + _i * 8192), 16, 0, 0); } while (0)
; #define PG8_LDA(dst, b, h) do { _Pragma("unroll") for (int m = 0; m < 4; ++m) _Pragma("unroll") for (int k = 0; k < 2; ++k) dst[m][k] = *(const LAS bf16x8*)(lds + PG8_SA(b, h) + aoff + m * 2048 + k * 1024); } while (0)
; #define PG8_WAIT_V(n) asm volatile("s_waitcnt vmcnt(" #n ")" ::: "memory")
; #define PG8_WAIT_L(n) asm volatile("s_waitcnt lgkmcnt(" #n ")" ::: "memory")
; template <class Prog>
; __device__ __forceinline__ void gemm_phase(LAS unsigned char* lds, const int K, const Prog& S) {
;     ...
;         for (int t = 0; t < nt; t += 2) {
;             const bool last = (t == nt - 2);
;             const char* a1 = cA + (size_t)(t + 1) * kstep;
;             const char* a2 = last ? nA : cA + (size_t)(t + 2) * kstep; const char* b2 = last ? nB : cB + (size_t)(t + 2) * kstep;
;             const char* a3 = a2 + kstep; const char* b3 = b2 + kstep;
;             PG8_LDB(B0, 0, 0); PG8_SCHED; PG8_LDA(At, 0, 0); PG8_STAGE(PG8_SA(1, 1), a1 + hstep, voffA);
;             PG8_WAIT_L(8); PG8_BAR; PG8_WAIT_L(0); PG8_MMA(0, 0, At, B0); PG8_BAR; PG8_SCHED;
;             PG8_LDB(B1, 0, 1); PG8_STAGE(PG8_SB(0, 0), b2, voffB);
;             PG8_BAR; PG8_WAIT_L(0); PG8_MMA(0, 1, At, B1); PG8_BAR;
;             PG8_LDA(At, 0, 1); PG8_STAGE(PG8_SA(0, 0), a2, voffA);
;             PG8_BAR; PG8_WAIT_L(0); PG8_MMA(1, 0, At, B0); PG8_BAR; PG8_SCHED;
;             PG8_STAGE(PG8_SB(0, 1), b2 + hstep, voffB);
;             PG8_WAIT_V(6); PG8_BAR; PG8_MMA(1, 1, At, B1); PG8_BAR;
;             PG8_LDB(B0, 1, 0); PG8_SCHED; PG8_LDA(At, 1, 0); PG8_STAGE(PG8_SA(0, 1), a2 + hstep, voffA);
;             PG8_WAIT_L(8); PG8_BAR; PG8_WAIT_L(0); PG8_MMA(0, 0, At, B0); PG8_BAR; PG8_SCHED;
;             PG8_LDB(B1, 1, 1); PG8_STAGE(PG8_SB(1, 0), b3, voffB);
;             PG8_BAR; PG8_WAIT_L(0); PG8_MMA(0, 1, At, B1); PG8_BAR;
;             PG8_LDA(At, 1, 1); PG8_STAGE(PG8_SA(1, 0), a3, voffA);
;             PG8_BAR; PG8_WAIT_L(0); PG8_MMA(1, 0, At, B0); PG8_BAR; PG8_SCHED;
;             PG8_STAGE(PG8_SB(1, 1), b3 + hstep, voffB);
;             PG8_WAIT_V(6); PG8_BAR; PG8_MMA(1, 1, At, B1); PG8_BAR;
.LBB0_571:
	ds_read_b128 v[128:131], v202
	ds_read_b128 v[132:135], v202 offset:1024
	ds_read_b128 v[136:139], v202 offset:2048
	ds_read_b128 v[140:143], v202 offset:3072
	s_add_i32 m0, s75, 0x8000
	ds_read_b128 v[176:179], v202 offset:16384
	ds_read_b128 v[180:183], v202 offset:17408
	ds_read_b128 v[184:187], v202 offset:18432
	ds_read_b128 v[198:201], v202 offset:19456
	global_load_lds_dwordx4 v190, s[100:101]
	s_add_i32 m0, s75, 0xa000
	ds_read_b128 v[144:147], v217
	ds_read_b128 v[148:151], v217 offset:1024
	ds_read_b128 v[152:155], v217 offset:2048
	ds_read_b128 v[156:159], v217 offset:3072
	global_load_lds_dwordx4 v196, s[100:101]
	s_add_i32 m0, s75, 0xc000
	ds_read_b128 v[160:163], v217 offset:4096
	ds_read_b128 v[164:167], v217 offset:5120
	ds_read_b128 v[168:171], v217 offset:6144
	ds_read_b128 v[172:175], v217 offset:7168
	global_load_lds_dwordx4 v190, s[46:47]
	s_add_i32 m0, s75, 0xe000
	s_nop 0
	global_load_lds_dwordx4 v196, s[46:47]
	s_waitcnt lgkmcnt(0)
	s_barrier
	v_mfma_f32_16x16x32_bf16 v[124:127], v[128:131], v[144:147], v[124:127]
	v_mfma_f32_16x16x32_bf16 v[120:123], v[136:139], v[144:147], v[120:123]
	v_mfma_f32_16x16x32_bf16 v[108:111], v[128:131], v[152:155], v[108:111]
	v_mfma_f32_16x16x32_bf16 v[104:107], v[136:139], v[152:155], v[104:107]
	v_mfma_f32_16x16x32_bf16 v[92:95], v[128:131], v[160:163], v[92:95]
	v_mfma_f32_16x16x32_bf16 v[88:91], v[136:139], v[160:163], v[88:91]
	v_mfma_f32_16x16x32_bf16 v[76:79], v[128:131], v[168:171], v[76:79]
	v_mfma_f32_16x16x32_bf16 v[72:75], v[136:139], v[168:171], v[72:75]
	v_mfma_f32_16x16x32_bf16 v[124:127], v[132:135], v[148:151], v[124:127]
	v_mfma_f32_16x16x32_bf16 v[120:123], v[140:143], v[148:151], v[120:123]
	v_mfma_f32_16x16x32_bf16 v[108:111], v[132:135], v[156:159], v[108:111]
	v_mfma_f32_16x16x32_bf16 v[104:107], v[140:143], v[156:159], v[104:107]
	v_mfma_f32_16x16x32_bf16 v[92:95], v[132:135], v[164:167], v[92:95]
	v_mfma_f32_16x16x32_bf16 v[88:91], v[140:143], v[164:167], v[88:91]
	v_mfma_f32_16x16x32_bf16 v[76:79], v[132:135], v[172:175], v[76:79]
	v_mfma_f32_16x16x32_bf16 v[72:75], v[140:143], v[172:175], v[72:75]
	v_mfma_f32_16x16x32_bf16 v[116:119], v[176:179], v[144:147], v[116:119]
	v_mfma_f32_16x16x32_bf16 v[112:115], v[184:187], v[144:147], v[112:115]
	v_mfma_f32_16x16x32_bf16 v[100:103], v[176:179], v[152:155], v[100:103]
	v_mfma_f32_16x16x32_bf16 v[96:99], v[184:187], v[152:155], v[96:99]
	v_mfma_f32_16x16x32_bf16 v[84:87], v[176:179], v[160:163], v[84:87]
	v_mfma_f32_16x16x32_bf16 v[80:83], v[184:187], v[160:163], v[80:83]
	v_mfma_f32_16x16x32_bf16 v[68:71], v[176:179], v[168:171], v[68:71]
	v_mfma_f32_16x16x32_bf16 v[64:67], v[184:187], v[168:171], v[64:67]
	v_mfma_f32_16x16x32_bf16 v[116:119], v[180:183], v[148:151], v[116:119]
	v_mfma_f32_16x16x32_bf16 v[112:115], v[198:201], v[148:151], v[112:115]
	v_mfma_f32_16x16x32_bf16 v[100:103], v[180:183], v[156:159], v[100:103]
	v_mfma_f32_16x16x32_bf16 v[96:99], v[198:201], v[156:159], v[96:99]
	v_mfma_f32_16x16x32_bf16 v[84:87], v[180:183], v[164:167], v[84:87]
	v_mfma_f32_16x16x32_bf16 v[80:83], v[198:201], v[164:167], v[80:83]
	v_mfma_f32_16x16x32_bf16 v[68:71], v[180:183], v[172:175], v[68:71]
	v_mfma_f32_16x16x32_bf16 v[64:67], v[198:201], v[172:175], v[64:67]
	s_add_u32 vcc_lo, s52, 0x80000
	s_addc_u32 vcc_hi, s53, 0
	s_add_u32 s98, s92, 0x80000
	s_addc_u32 s99, s93, 0
	s_barrier
	ds_read_b128 v[144:147], v217 offset:16384
	ds_read_b128 v[148:151], v217 offset:17408
	ds_read_b128 v[152:155], v217 offset:18432
	ds_read_b128 v[156:159], v217 offset:19456
	s_add_i32 m0, s75, 0x10000
	ds_read_b128 v[160:163], v217 offset:20480
	ds_read_b128 v[164:167], v217 offset:21504
	ds_read_b128 v[168:171], v217 offset:22528
	ds_read_b128 v[172:175], v217 offset:23552
	global_load_lds_dwordx4 v192, s[52:53]
	s_add_i32 m0, s75, 0x12000
	s_nop 0
	global_load_lds_dwordx4 v188, s[52:53]
	s_add_i32 m0, s75, 0x14000
	s_nop 0
	global_load_lds_dwordx4 v192, vcc
	s_add_i32 m0, s75, 0x16000
	s_nop 0
	global_load_lds_dwordx4 v188, vcc
	s_waitcnt vmcnt(4)
	s_waitcnt lgkmcnt(0)
	s_barrier
	v_mfma_f32_16x16x32_bf16 v[60:63], v[128:131], v[144:147], v[60:63]
	v_mfma_f32_16x16x32_bf16 v[56:59], v[136:139], v[144:147], v[56:59]
	v_mfma_f32_16x16x32_bf16 v[44:47], v[128:131], v[152:155], v[44:47]
	v_mfma_f32_16x16x32_bf16 v[40:43], v[136:139], v[152:155], v[40:43]
	v_mfma_f32_16x16x32_bf16 v[28:31], v[128:131], v[160:163], v[28:31]
	v_mfma_f32_16x16x32_bf16 v[24:27], v[136:139], v[160:163], v[24:27]
	v_mfma_f32_16x16x32_bf16 v[12:15], v[128:131], v[168:171], v[12:15]
	v_mfma_f32_16x16x32_bf16 v[8:11], v[136:139], v[168:171], v[8:11]
	v_mfma_f32_16x16x32_bf16 v[60:63], v[132:135], v[148:151], v[60:63]
	v_mfma_f32_16x16x32_bf16 v[56:59], v[140:143], v[148:151], v[56:59]
	v_mfma_f32_16x16x32_bf16 v[44:47], v[132:135], v[156:159], v[44:47]
	v_mfma_f32_16x16x32_bf16 v[40:43], v[140:143], v[156:159], v[40:43]
	v_mfma_f32_16x16x32_bf16 v[28:31], v[132:135], v[164:167], v[28:31]
	v_mfma_f32_16x16x32_bf16 v[24:27], v[140:143], v[164:167], v[24:27]
	v_mfma_f32_16x16x32_bf16 v[12:15], v[132:135], v[172:175], v[12:15]
	v_mfma_f32_16x16x32_bf16 v[8:11], v[140:143], v[172:175], v[8:11]
	v_mfma_f32_16x16x32_bf16 v[52:55], v[176:179], v[144:147], v[52:55]
	v_mfma_f32_16x16x32_bf16 v[48:51], v[184:187], v[144:147], v[48:51]
	v_mfma_f32_16x16x32_bf16 v[36:39], v[176:179], v[152:155], v[36:39]
	v_mfma_f32_16x16x32_bf16 v[32:35], v[184:187], v[152:155], v[32:35]
	v_mfma_f32_16x16x32_bf16 v[20:23], v[176:179], v[160:163], v[20:23]
	v_mfma_f32_16x16x32_bf16 v[16:19], v[184:187], v[160:163], v[16:19]
	v_mfma_f32_16x16x32_bf16 v[4:7], v[176:179], v[168:171], v[4:7]
	v_mfma_f32_16x16x32_bf16 v[0:3], v[184:187], v[168:171], v[0:3]
	v_mfma_f32_16x16x32_bf16 v[52:55], v[180:183], v[148:151], v[52:55]
	v_mfma_f32_16x16x32_bf16 v[48:51], v[198:201], v[148:151], v[48:51]
	v_mfma_f32_16x16x32_bf16 v[36:39], v[180:183], v[156:159], v[36:39]
	v_mfma_f32_16x16x32_bf16 v[32:35], v[198:201], v[156:159], v[32:35]
	v_mfma_f32_16x16x32_bf16 v[20:23], v[180:183], v[164:167], v[20:23]
	v_mfma_f32_16x16x32_bf16 v[16:19], v[198:201], v[164:167], v[16:19]
	v_mfma_f32_16x16x32_bf16 v[4:7], v[180:183], v[172:175], v[4:7]
	v_mfma_f32_16x16x32_bf16 v[0:3], v[198:201], v[172:175], v[0:3]
	s_barrier
; #define PG8_STAGE(bufoff, gbase, voff) do { _Pragma("unroll") for (int _i = 0; _i < 2; ++_i) \
;         __builtin_amdgcn_global_load_lds((const unsigned*)((const char*)(gbase) + (voff)[_i]), (LAS unsigned*)(lds + (bufoff) + ldsw + _i * 8192), 16, 0, 0); } while (0)
; #define PG8_LDA(dst, b, h) do { _Pragma("unroll") for (int m = 0; m < 4; ++m) _Pragma("unroll") for (int k = 0; k < 2; ++k) dst[m][k] = *(const LAS bf16x8*)(lds + PG8_SA(b, h) + aoff + m * 2048 + k * 1024); } while (0)
; #define PG8_WAIT_V(n) asm volatile("s_waitcnt vmcnt(" #n ")" ::: "memory")
; #define PG8_WAIT_L(n) asm volatile("s_waitcnt lgkmcnt(" #n ")" ::: "memory")
; template <class Prog>
; __device__ __forceinline__ void gemm_phase(LAS unsigned char* lds, const int K, const Prog& S) {
;     ...
;         for (int t = 0; t < nt; t += 2) {
;             const bool last = (t == nt - 2);
;             const char* a1 = cA + (size_t)(t + 1) * kstep;
;             const char* a2 = last ? nA : cA + (size_t)(t + 2) * kstep; const char* b2 = last ? nB : cB + (size_t)(t + 2) * kstep;
;             const char* a3 = a2 + kstep; const char* b3 = b2 + kstep;
;             PG8_LDB(B0, 0, 0); PG8_SCHED; PG8_LDA(At, 0, 0); PG8_STAGE(PG8_SA(1, 1), a1 + hstep, voffA);
;             PG8_WAIT_L(8); PG8_BAR; PG8_WAIT_L(0); PG8_MMA(0, 0, At, B0); PG8_BAR; PG8_SCHED;
;             PG8_LDB(B1, 0, 1); PG8_STAGE(PG8_SB(0, 0), b2, voffB);
;             PG8_BAR; PG8_WAIT_L(0); PG8_MMA(0, 1, At, B1); PG8_BAR;
;             PG8_LDA(At, 0, 1); PG8_STAGE(PG8_SA(0, 0), a2, voffA);
;             PG8_BAR; PG8_WAIT_L(0); PG8_MMA(1, 0, At, B0); PG8_BAR; PG8_SCHED;
;             PG8_STAGE(PG8_SB(0, 1), b2 + hstep, voffB);
;             PG8_WAIT_V(6); PG8_BAR; PG8_MMA(1, 1, At, B1); PG8_BAR;
;             PG8_LDB(B0, 1, 0); PG8_SCHED; PG8_LDA(At, 1, 0); PG8_STAGE(PG8_SA(0, 1), a2 + hstep, voffA);
;             PG8_WAIT_L(8); PG8_BAR; PG8_WAIT_L(0); PG8_MMA(0, 0, At, B0); PG8_BAR; PG8_SCHED;
;             PG8_LDB(B1, 1, 1); PG8_STAGE(PG8_SB(1, 0), b3, voffB);
;             PG8_BAR; PG8_WAIT_L(0); PG8_MMA(0, 1, At, B1); PG8_BAR;
;             PG8_LDA(At, 1, 1); PG8_STAGE(PG8_SA(1, 0), a3, voffA);
;             PG8_BAR; PG8_WAIT_L(0); PG8_MMA(1, 0, At, B0); PG8_BAR; PG8_SCHED;
;             PG8_STAGE(PG8_SB(1, 1), b3 + hstep, voffB);
;             PG8_WAIT_V(6); PG8_BAR; PG8_MMA(1, 1, At, B1); PG8_BAR;
	ds_read_b128 v[128:131], v202 offset:32768
	ds_read_b128 v[132:135], v202 offset:33792
	ds_read_b128 v[136:139], v202 offset:34816
	ds_read_b128 v[140:143], v202 offset:35840
	s_mov_b32 m0, s75
	ds_read_b128 v[176:179], v202 offset:49152
	ds_read_b128 v[180:183], v202 offset:50176
	ds_read_b128 v[184:187], v202 offset:51200
	ds_read_b128 v[198:201], v202 offset:52224
	global_load_lds_dwordx4 v192, s[92:93]
	s_add_i32 m0, s75, 0x2000
	ds_read_b128 v[144:147], v217 offset:32768
	ds_read_b128 v[148:151], v217 offset:33792
	ds_read_b128 v[152:155], v217 offset:34816
	ds_read_b128 v[156:159], v217 offset:35840
	global_load_lds_dwordx4 v188, s[92:93]
	s_add_i32 m0, s75, 0x4000
	ds_read_b128 v[160:163], v217 offset:36864
	ds_read_b128 v[164:167], v217 offset:37888
	ds_read_b128 v[168:171], v217 offset:38912
	ds_read_b128 v[172:175], v217 offset:39936
	global_load_lds_dwordx4 v192, s[98:99]
	s_add_i32 m0, s75, 0x6000
	s_nop 0
	global_load_lds_dwordx4 v188, s[98:99]
	s_waitcnt lgkmcnt(0)
	s_barrier
	v_mfma_f32_16x16x32_bf16 v[124:127], v[128:131], v[144:147], v[124:127]
	v_mfma_f32_16x16x32_bf16 v[120:123], v[136:139], v[144:147], v[120:123]
	v_mfma_f32_16x16x32_bf16 v[108:111], v[128:131], v[152:155], v[108:111]
	v_mfma_f32_16x16x32_bf16 v[104:107], v[136:139], v[152:155], v[104:107]
	v_mfma_f32_16x16x32_bf16 v[92:95], v[128:131], v[160:163], v[92:95]
	v_mfma_f32_16x16x32_bf16 v[88:91], v[136:139], v[160:163], v[88:91]
	v_mfma_f32_16x16x32_bf16 v[76:79], v[128:131], v[168:171], v[76:79]
	v_mfma_f32_16x16x32_bf16 v[72:75], v[136:139], v[168:171], v[72:75]
	v_mfma_f32_16x16x32_bf16 v[124:127], v[132:135], v[148:151], v[124:127]
	v_mfma_f32_16x16x32_bf16 v[120:123], v[140:143], v[148:151], v[120:123]
	v_mfma_f32_16x16x32_bf16 v[108:111], v[132:135], v[156:159], v[108:111]
	v_mfma_f32_16x16x32_bf16 v[104:107], v[140:143], v[156:159], v[104:107]
	v_mfma_f32_16x16x32_bf16 v[92:95], v[132:135], v[164:167], v[92:95]
	v_mfma_f32_16x16x32_bf16 v[88:91], v[140:143], v[164:167], v[88:91]
	v_mfma_f32_16x16x32_bf16 v[76:79], v[132:135], v[172:175], v[76:79]
	v_mfma_f32_16x16x32_bf16 v[72:75], v[140:143], v[172:175], v[72:75]
	v_mfma_f32_16x16x32_bf16 v[116:119], v[176:179], v[144:147], v[116:119]
	v_mfma_f32_16x16x32_bf16 v[112:115], v[184:187], v[144:147], v[112:115]
	v_mfma_f32_16x16x32_bf16 v[100:103], v[176:179], v[152:155], v[100:103]
	v_mfma_f32_16x16x32_bf16 v[96:99], v[184:187], v[152:155], v[96:99]
	v_mfma_f32_16x16x32_bf16 v[84:87], v[176:179], v[160:163], v[84:87]
	v_mfma_f32_16x16x32_bf16 v[80:83], v[184:187], v[160:163], v[80:83]
	v_mfma_f32_16x16x32_bf16 v[68:71], v[176:179], v[168:171], v[68:71]
	v_mfma_f32_16x16x32_bf16 v[64:67], v[184:187], v[168:171], v[64:67]
	v_mfma_f32_16x16x32_bf16 v[116:119], v[180:183], v[148:151], v[116:119]
	v_mfma_f32_16x16x32_bf16 v[112:115], v[198:201], v[148:151], v[112:115]
	v_mfma_f32_16x16x32_bf16 v[100:103], v[180:183], v[156:159], v[100:103]
	v_mfma_f32_16x16x32_bf16 v[96:99], v[198:201], v[156:159], v[96:99]
	v_mfma_f32_16x16x32_bf16 v[84:87], v[180:183], v[164:167], v[84:87]
	v_mfma_f32_16x16x32_bf16 v[80:83], v[198:201], v[164:167], v[80:83]
	v_mfma_f32_16x16x32_bf16 v[68:71], v[180:183], v[172:175], v[68:71]
	v_mfma_f32_16x16x32_bf16 v[64:67], v[198:201], v[172:175], v[64:67]
	s_add_u32 vcc_lo, s52, 0x80
	s_addc_u32 vcc_hi, s53, 0
	s_add_u32 s98, s52, 0x80080
	s_addc_u32 s99, s53, 0
	s_add_i32 s54, s54, 2
	s_add_u32 s46, s46, 0x100
	s_addc_u32 s47, s47, 0
	s_add_u32 s41, s41, 0x100
	s_addc_u32 s43, s43, 0
	s_add_u32 s52, s46, 0xfff80080
	s_addc_u32 s53, s47, -1
	s_cmp_eq_u32 s54, 28
	s_cselect_b32 s93, s7, s53
	s_cselect_b32 s92, s6, s52
	s_cselect_b32 s53, s45, s43
	s_cselect_b32 s52, s44, s41
	s_add_u32 s100, s46, 0xfff80000
	s_addc_u32 s101, s47, -1
	s_barrier
	ds_read_b128 v[144:147], v217 offset:49152
	ds_read_b128 v[148:151], v217 offset:50176
	ds_read_b128 v[152:155], v217 offset:51200
	ds_read_b128 v[156:159], v217 offset:52224
	s_add_i32 m0, s75, 0x18000
	ds_read_b128 v[160:163], v217 offset:53248
	ds_read_b128 v[164:167], v217 offset:54272
	ds_read_b128 v[168:171], v217 offset:55296
	ds_read_b128 v[172:175], v217 offset:56320
	global_load_lds_dwordx4 v192, vcc
	s_add_i32 m0, s75, 0x1a000
	s_nop 0
	global_load_lds_dwordx4 v188, vcc
	s_add_i32 m0, s75, 0x1c000
	s_nop 0
	global_load_lds_dwordx4 v192, s[98:99]
	s_add_i32 m0, s75, 0x1e000
	s_nop 0
	global_load_lds_dwordx4 v188, s[98:99]
	s_waitcnt vmcnt(4)
	s_waitcnt lgkmcnt(0)
	s_barrier
; template <class Prog>
; __device__ __forceinline__ void gemm_phase(LAS unsigned char* lds, const int K, const Prog& S) {
;     ...
;         for (int t = 0; t < nt; t += 2) {
;             const bool last = (t == nt - 2);
;             const char* a1 = cA + (size_t)(t + 1) * kstep;
;             const char* a2 = last ? nA : cA + (size_t)(t + 2) * kstep; const char* b2 = last ? nB : cB + (size_t)(t + 2) * kstep;
;             const char* a3 = a2 + kstep; const char* b3 = b2 + kstep;
;             PG8_LDB(B0, 0, 0); PG8_SCHED; PG8_LDA(At, 0, 0); PG8_STAGE(PG8_SA(1, 1), a1 + hstep, voffA);
;             PG8_WAIT_L(8); PG8_BAR; PG8_WAIT_L(0); PG8_MMA(0, 0, At, B0); PG8_BAR; PG8_SCHED;
;             PG8_LDB(B1, 0, 1); PG8_STAGE(PG8_SB(0, 0), b2, voffB);
;             PG8_BAR; PG8_WAIT_L(0); PG8_MMA(0, 1, At, B1); PG8_BAR;
;             PG8_LDA(At, 0, 1); PG8_STAGE(PG8_SA(0, 0), a2, voffA);
;             PG8_BAR; PG8_WAIT_L(0); PG8_MMA(1, 0, At, B0); PG8_BAR; PG8_SCHED;
;             PG8_STAGE(PG8_SB(0, 1), b2 + hstep, voffB);
;             PG8_WAIT_V(6); PG8_BAR; PG8_MMA(1, 1, At, B1); PG8_BAR;
;             PG8_LDB(B0, 1, 0); PG8_SCHED; PG8_LDA(At, 1, 0); PG8_STAGE(PG8_SA(0, 1), a2 + hstep, voffA);
;             PG8_WAIT_L(8); PG8_BAR; PG8_WAIT_L(0); PG8_MMA(0, 0, At, B0); PG8_BAR; PG8_SCHED;
;             PG8_LDB(B1, 1, 1); PG8_STAGE(PG8_SB(1, 0), b3, voffB);
;             PG8_BAR; PG8_WAIT_L(0); PG8_MMA(0, 1, At, B1); PG8_BAR;
;             PG8_LDA(At, 1, 1); PG8_STAGE(PG8_SA(1, 0), a3, voffA);
;             PG8_BAR; PG8_WAIT_L(0); PG8_MMA(1, 0, At, B0); PG8_BAR; PG8_SCHED;
;             PG8_STAGE(PG8_SB(1, 1), b3 + hstep, voffB);
;             PG8_WAIT_V(6); PG8_BAR; PG8_MMA(1, 1, At, B1); PG8_BAR;
;     __device__ __forceinline__ void epi(f32x4 (&acc)[2][2][4][2], const pg8::Unit& u, int wr, int wc, int fr, int fq) const {
;         const int row0 = u.pm * 256 + wr * 64 + fr, col0 = u.pn * 256 + wc * 32 + 4 * fq;
; #pragma unroll
;         for (int ai = 0; ai < 2; ++ai) {
;             f32x4 xo[4][2][2];
; #pragma unroll
;             for (int m = 0; m < 4; ++m)
; #pragma unroll
;                 for (int bj = 0; bj < 2; ++bj)
; #pragma unroll
;                     for (int n = 0; n < 2; ++n) xo[m][bj][n] = *(const f32x4*)(xin + (size_t)(row0 + ai * 128 + m * 16) * DM + col0 + bj * 128 + n * 16);
; #pragma unroll
;             for (int m = 0; m < 4; ++m) {
	v_mfma_f32_16x16x32_bf16 v[60:63], v[128:131], v[144:147], v[60:63]
	v_mfma_f32_16x16x32_bf16 v[56:59], v[136:139], v[144:147], v[56:59]
	v_mfma_f32_16x16x32_bf16 v[44:47], v[128:131], v[152:155], v[44:47]
	v_mfma_f32_16x16x32_bf16 v[40:43], v[136:139], v[152:155], v[40:43]
	v_mfma_f32_16x16x32_bf16 v[28:31], v[128:131], v[160:163], v[28:31]
	v_mfma_f32_16x16x32_bf16 v[24:27], v[136:139], v[160:163], v[24:27]
	v_mfma_f32_16x16x32_bf16 v[12:15], v[128:131], v[168:171], v[12:15]
	v_mfma_f32_16x16x32_bf16 v[8:11], v[136:139], v[168:171], v[8:11]
	v_mfma_f32_16x16x32_bf16 v[60:63], v[132:135], v[148:151], v[60:63]
	v_mfma_f32_16x16x32_bf16 v[56:59], v[140:143], v[148:151], v[56:59]
	v_mfma_f32_16x16x32_bf16 v[44:47], v[132:135], v[156:159], v[44:47]
	v_mfma_f32_16x16x32_bf16 v[40:43], v[140:143], v[156:159], v[40:43]
	v_mfma_f32_16x16x32_bf16 v[28:31], v[132:135], v[164:167], v[28:31]
	v_mfma_f32_16x16x32_bf16 v[24:27], v[140:143], v[164:167], v[24:27]
	v_mfma_f32_16x16x32_bf16 v[12:15], v[132:135], v[172:175], v[12:15]
	v_mfma_f32_16x16x32_bf16 v[8:11], v[140:143], v[172:175], v[8:11]
	v_mfma_f32_16x16x32_bf16 v[52:55], v[176:179], v[144:147], v[52:55]
	v_mfma_f32_16x16x32_bf16 v[48:51], v[184:187], v[144:147], v[48:51]
	v_mfma_f32_16x16x32_bf16 v[36:39], v[176:179], v[152:155], v[36:39]
	v_mfma_f32_16x16x32_bf16 v[32:35], v[184:187], v[152:155], v[32:35]
	v_mfma_f32_16x16x32_bf16 v[20:23], v[176:179], v[160:163], v[20:23]
	v_mfma_f32_16x16x32_bf16 v[16:19], v[184:187], v[160:163], v[16:19]
	v_mfma_f32_16x16x32_bf16 v[4:7], v[176:179], v[168:171], v[4:7]
	v_mfma_f32_16x16x32_bf16 v[0:3], v[184:187], v[168:171], v[0:3]
	v_mfma_f32_16x16x32_bf16 v[52:55], v[180:183], v[148:151], v[52:55]
	v_mfma_f32_16x16x32_bf16 v[48:51], v[198:201], v[148:151], v[48:51]
	v_mfma_f32_16x16x32_bf16 v[36:39], v[180:183], v[156:159], v[36:39]
	v_mfma_f32_16x16x32_bf16 v[32:35], v[198:201], v[156:159], v[32:35]
	v_mfma_f32_16x16x32_bf16 v[20:23], v[180:183], v[164:167], v[20:23]
	v_mfma_f32_16x16x32_bf16 v[16:19], v[198:201], v[164:167], v[16:19]
	v_mfma_f32_16x16x32_bf16 v[4:7], v[180:183], v[172:175], v[4:7]
	v_mfma_f32_16x16x32_bf16 v[0:3], v[198:201], v[172:175], v[0:3]
	s_cmp_gt_u32 s54, 29
	s_barrier
	s_cbranch_scc0 .LBB0_571
	v_lshl_add_u32 v202, s80, 8, v214
	v_lshl_or_b32 v198, s73, 8, v216
	v_ashrrev_i32_e32 v199, 31, v198
	v_ashrrev_i32_e32 v203, 31, v202
	v_lshl_add_u64 v[200:201], v[198:199], 2, s[8:9]
	v_lshlrev_b64 v[128:129], 13, v[202:203]
	v_or_b32_e32 v208, 16, v202
	v_lshl_add_u64 v[128:129], v[200:201], 0, v[128:129]
	v_ashrrev_i32_e32 v209, 31, v208
	global_load_dwordx4 v[210:213], v[128:129], off
	global_load_dwordx4 v[184:187], v[128:129], off offset:64
	global_load_dwordx4 v[180:183], v[128:129], off offset:512
	global_load_dwordx4 v[176:179], v[128:129], off offset:576
	v_lshlrev_b64 v[128:129], 13, v[208:209]
	v_or_b32_e32 v206, 32, v202
	v_lshl_add_u64 v[128:129], v[200:201], 0, v[128:129]
	v_ashrrev_i32_e32 v207, 31, v206
	global_load_dwordx4 v[172:175], v[128:129], off
	global_load_dwordx4 v[168:171], v[128:129], off offset:64
	global_load_dwordx4 v[164:167], v[128:129], off offset:512
	global_load_dwordx4 v[160:163], v[128:129], off offset:576
	v_lshlrev_b64 v[128:129], 13, v[206:207]
	v_or_b32_e32 v204, 48, v202
	v_lshl_add_u64 v[128:129], v[200:201], 0, v[128:129]
	v_ashrrev_i32_e32 v205, 31, v204
	global_load_dwordx4 v[156:159], v[128:129], off
	global_load_dwordx4 v[152:155], v[128:129], off offset:64
	global_load_dwordx4 v[148:151], v[128:129], off offset:512
	global_load_dwordx4 v[144:147], v[128:129], off offset:576
	v_lshlrev_b64 v[128:129], 13, v[204:205]
	v_lshl_add_u64 v[128:129], v[200:201], 0, v[128:129]
	global_load_dwordx4 v[140:143], v[128:129], off
	global_load_dwordx4 v[136:139], v[128:129], off offset:64
	global_load_dwordx4 v[132:135], v[128:129], off offset:512
	s_nop 0
	global_load_dwordx4 v[128:131], v[128:129], off offset:576
	v_lshlrev_b64 v[218:219], 11, v[202:203]
	v_lshl_add_u64 v[218:219], v[218:219], 0, v[198:199]
	s_andn2_b64 vcc, exec, s[12:13]
	s_waitcnt vmcnt(0)
	v_pk_add_f32 v[126:127], v[126:127], v[212:213]
	v_cndmask_b32_e64 v212, 0, 1, s[12:13]
	v_pk_add_f32 v[124:125], v[124:125], v[210:211]
	v_lshl_add_u64 v[210:211], v[218:219], 2, s[48:49]
	v_cmp_ne_u32_e64 s[6:7], 1, v212
	v_lshl_add_u64 v[212:213], v[218:219], 1, s[20:21]
	global_store_dwordx4 v[210:211], v[124:127], off
	s_cbranch_vccnz .LBB0_574
	v_cvt_pk_bf16_f32 v218, v124, v125
	v_cvt_pk_bf16_f32 v219, v126, v127
	global_store_dwordx2 v[212:213], v[218:219], off
